# adds to previous: GA unit loop reads the w_gate_up/b_gate kernarg pointers once before the loop; GC per-row wave sums use DPP/permlane swaps in the same xor-butterfly order instead of ds_bpermute hops
# speedup vs baseline: 1.0012x; 1.0012x over previous
; #define LAS __attribute__((address_space(3)))
; #define w_gate_up ARGP(4)
; #define b_gate ARGP(5)
; __device__ __forceinline__ void ga_unit(LAS unsigned char* lds, int unit, bf16_t* proj, const float* glow, const float* w_gate_up, const float* b_gate, bf16_t* dSt, float* decay, int tid, int wave, int lane) {
;     const int n = unit & 63, bh = unit >> 6, b = bh >> 3, h = bh & 7;
;     const size_t row0 = (size_t)b * SEQ + n * 64;
;     const int k = tid & 127, seg = __builtin_amdgcn_readfirstlane(tid >> 7);
;     const int t = tid >> 3, c0 = (tid & 7) * 16;
;     bf16_t* qp = proj + (row0 + t) * PROJ_LD + C_GQ + h * 128 + c0; bf16_t* kp = qp + (C_GK - C_GQ);
;     const u32x4 q0 = *(const u32x4*)qp, q1 = *(const u32x4*)(qp + 8), k0 = *(const u32x4*)kp, k1 = *(const u32x4*)(kp + 8);
;     u32x4 vr[4]; load_v(vr, proj + row0 * PROJ_LD + C_GV + h * 256, tid);
;     float wg[16];
; #pragma unroll
;     for (int r = 0; r < 16; ++r) wg[r] = w_gate_up[r * 1024 + h * 128 + k];
; __global__ void __launch_bounds__(NWAVES * 64, 2) fwd(Args args) {
;     ...
;         { const int bx = (int)blockIdx.x; int u0, nu;
;           if (bx < 128) { u0 = bx * 4; nu = 4; } else { u0 = 512 + (bx - 128) * 12; nu = 12; }
;           for (int j = 0; j < nu; ++j) gla::ga_unit(F.lds, u0 + j, proj, glow, w_gate_up, b_gate, dSt, decay, F.tid, F.wave, F.lane); }
.LBB0_622:
	v_lshrrev_b32_e32 v8, 4, v0
	v_bfe_u32 v10, v0, 3, 2
	v_lshlrev_b32_e32 v7, 1, v130
	v_and_or_b32 v8, v8, 4, v10
	v_and_b32_e32 v2, 0x70, v131
	v_and_or_b32 v7, v7, 8, v150
	v_lshlrev_b32_e32 v10, 6, v8
	v_mul_u32_u24_e32 v8, 0x84, v130
	v_lshrrev_b32_e32 v7, 1, v7
	v_add_lshl_u32 v11, v8, v2, 2
	v_bfe_u32 v8, v131, 5, 2
	v_lshlrev_b32_e32 v3, 5, v0
	v_lshlrev_b32_e32 v5, 12, v0
	v_and_or_b32 v9, v0, 3, v7
	v_or_b32_e32 v7, v7, v8
	v_readlane_b32 s10, v254, 8
	v_and_b32_e32 v4, 0xe0, v3
	v_and_b32_e32 v5, 0x4000, v5
	v_lshlrev_b32_e32 v9, 9, v9
	v_lshlrev_b32_e32 v7, 9, v7
	v_and_b32_e32 v3, 32, v3
	s_lshl_b32 s4, s10, 12
	v_add3_u32 v5, 0, v5, v9
	v_add3_u32 v3, 0, v3, v7
	v_lshlrev_b32_e32 v7, 3, v0
	v_lshlrev_b32_e32 v9, 1, v0
	s_and_b32 s4, s4, 0x7fffc000
	v_and_b32_e32 v8, 0xc0, v131
	v_and_b32_e32 v9, 32, v9
	v_and_b32_e32 v7, 0x118, v7
	s_add_i32 s4, s4, 0
	v_or3_b32 v7, v9, v8, v7
	s_add_i32 s4, s4, 0xd800
	v_add_u32_e32 v58, s4, v7
	v_readlane_b32 s4, v254, 0
	s_bfe_u32 s28, s4, 0x20006
	s_add_i32 s4, 0, 0x9800
	s_ashr_i32 s7, s6, 31
	v_add_u32_e32 v59, s4, v7
	s_lshl_b64 s[4:5], s[6:7], 9
	v_and_b32_e32 v56, 0x7f, v0
	s_add_u32 s4, s78, s4
	v_mov_b32_e32 v35, 0
	v_lshlrev_b32_e32 v34, 2, v56
	v_and_b32_e32 v7, 31, v0
	v_lshrrev_b32_e32 v8, 1, v182
	s_addc_u32 s5, s79, s5
	v_add_u32_e32 v57, 0, v34
	v_and_b32_e32 v12, 16, v8
	v_lshl_add_u64 v[8:9], s[4:5], 0, v[34:35]
	s_mov_b64 s[4:5], 0x4e400000
	v_lshl_or_b32 v34, s10, 5, v7
	v_lshl_add_u64 v[36:37], v[8:9], 0, s[4:5]
	s_lshl_b64 s[4:5], s[6:7], 16
	v_lshlrev_b64 v[8:9], 8, v[34:35]
	v_and_b32_e32 v7, 32, v0
	v_lshl_add_u64 v[8:9], s[4:5], 0, v[8:9]
	v_lshrrev_b32_e32 v7, 1, v7
	v_or_b32_e32 v8, v8, v7
	v_mul_u32_u24_e32 v6, 0x1800, v130
	v_lshl_add_u64 v[8:9], s[76:77], 0, v[8:9]
	s_mov_b64 s[4:5], 0x80
	s_mov_b32 s11, 0
	s_movk_i32 s27, 0x4000
	s_lshl_b32 s29, s6, 6
	v_lshl_add_u64 v[38:39], v[8:9], 0, s[4:5]
	v_mov_b64_e32 v[40:41], s[92:93]
	s_movk_i32 s7, 0x3000
	v_mov_b64_e32 v[42:43], s[90:91]
	v_mov_b32_e32 v60, 0x3000
	v_lshlrev_b32_e32 v44, 1, v2
	v_mov_b32_e32 v45, v35
	v_lshlrev_b32_e32 v46, 1, v6
	v_mov_b32_e32 v47, v35
	v_lshlrev_b32_e32 v48, 1, v4
	v_mov_b32_e32 v49, v35
	s_mov_b64 s[12:13], 0x1000
	s_movk_i32 s30, 0x1000
	s_movk_i32 s31, 0x2000
	s_movk_i32 s33, 0x5000
	s_movk_i32 s34, 0x6000
	s_movk_i32 s35, 0x7000
	s_mov_b32 s36, 0x8000
	s_mov_b32 s37, 0x9000
	s_mov_b32 s38, 0xa000
	s_mov_b32 s39, 0xb000
	s_mov_b32 s40, 0xc000
	s_mov_b32 s41, 0xd000
	s_mov_b32 s42, 0xe000
	s_mov_b32 s43, 0xf000
	s_mov_b32 s44, 0xbfb8aa3b
	s_mov_b32 s45, 0x800000
	s_mov_b32 s46, 0x3f317217
	s_mov_b32 s47, 0x7f800000
	v_mov_b32_e32 v61, 0x41b17218
	s_mov_b32 s48, 0x3d800000
	v_add_u32_e32 v62, v5, v10
	v_add_u32_e32 v63, 0, v11
	v_add_u32_e32 v64, v3, v10
	v_add_u32_e32 v65, 0, v12
	s_mov_b64 s[18:19], 0x200
	s_mov_b64 s[20:21], 0x10000
	flat_load_dwordx2 v[250:251], v[40:41] offset:32 sc0 sc1
	flat_load_dwordx2 v[252:253], v[40:41] offset:40 sc0 sc1
	s_waitcnt vmcnt(0) lgkmcnt(0)
	s_branch .LBB0_624

; #define LAS __attribute__((address_space(3)))
; #define w_gate_up ARGP(4)
; #define b_gate ARGP(5)
; __device__ __forceinline__ float prep_b(LAS unsigned char* lds, const float* glow_rows, const float (&wg)[16], float bg, int k, int seg, float (&bv)[16]) {
;     float cum = 0.f;
; #pragma unroll
;     for (int j = 0; j < 16; ++j) { const float* gl = glow_rows + (16 * seg + j) * 16; float z = bg;
; #pragma unroll
;         for (int r = 0; r < 16; ++r) z += gl[r] * wg[r];
; __device__ __forceinline__ void ga_unit(LAS unsigned char* lds, int unit, bf16_t* proj, const float* glow, const float* w_gate_up, const float* b_gate, bf16_t* dSt, float* decay, int tid, int wave, int lane) {
;     const int n = unit & 63, bh = unit >> 6, b = bh >> 3, h = bh & 7;
;     const size_t row0 = (size_t)b * SEQ + n * 64;
;     const int k = tid & 127, seg = __builtin_amdgcn_readfirstlane(tid >> 7);
;     const int t = tid >> 3, c0 = (tid & 7) * 16;
;     bf16_t* qp = proj + (row0 + t) * PROJ_LD + C_GQ + h * 128 + c0; bf16_t* kp = qp + (C_GK - C_GQ);
;     const u32x4 q0 = *(const u32x4*)qp, q1 = *(const u32x4*)(qp + 8), k0 = *(const u32x4*)kp, k1 = *(const u32x4*)(kp + 8);
;     u32x4 vr[4]; load_v(vr, proj + row0 * PROJ_LD + C_GV + h * 256, tid);
;     float wg[16];
; #pragma unroll
;     for (int r = 0; r < 16; ++r) wg[r] = w_gate_up[r * 1024 + h * 128 + k];
;     float bv[16];
;     const float tot = prep_b(lds, glow + row0 * 16, wg, b_gate[h * 128 + k], k, seg, bv);
.LBB0_624:
	v_mov_b32_e32 v2, v250
	v_mov_b32_e32 v3, v251
	v_mov_b32_e32 v4, v252
	v_mov_b32_e32 v5, v253
	s_ashr_i32 s4, s6, 9
	s_ashr_i32 s5, s4, 31
	s_and_b32 s23, s29, 0xfc0
	s_lshl_b64 s[4:5], s[4:5], 12
	s_or_b32 s4, s4, s23
	s_bfe_u32 s22, s6, 0x30006
	s_mul_i32 s23, s5, 0x3000
	s_mul_hi_u32 s24, s4, 0x3000
	s_lshl_b32 s10, s22, 8
	s_mul_i32 s25, s4, 0x3000
	s_add_i32 s24, s24, s23
	s_add_u32 s23, s90, s25
	s_addc_u32 s25, s91, s24
	s_lshl_b32 s22, s22, 9
	v_lshl_or_b32 v34, v56, 2, s22
	v_readfirstlane_b32 s49, v0
	s_add_u32 s24, s23, s22
	s_addc_u32 s25, s25, 0
	s_lshr_b32 s50, s49, 7
	s_lshl_b64 s[22:23], s[4:5], 6
	s_add_u32 s51, s16, s22
	s_addc_u32 s52, s17, s23
	s_lshl_b32 s22, s50, 8
	s_ashr_i32 s23, s22, 31
	s_lshl_b64 s[22:23], s[22:23], 2
	s_add_u32 s22, s51, s22
	s_addc_u32 s23, s52, s23
	s_cmpk_lt_u32 s49, 0x80
	s_waitcnt lgkmcnt(0)
	v_lshl_add_u64 v[2:3], v[2:3], 0, v[34:35]
	v_add_co_u32_e32 v6, vcc, s30, v2
	v_lshl_add_u64 v[4:5], v[4:5], 0, v[34:35]
	s_nop 0
	v_addc_co_u32_e32 v7, vcc, 0, v3, vcc
	v_add_co_u32_e32 v8, vcc, s31, v2
	s_nop 1
	v_addc_co_u32_e32 v9, vcc, 0, v3, vcc
	v_add_co_u32_e32 v10, vcc, s7, v2
	s_nop 1
	v_addc_co_u32_e32 v11, vcc, 0, v3, vcc
	v_add_co_u32_e32 v12, vcc, s27, v2
	s_nop 1
	v_addc_co_u32_e32 v13, vcc, 0, v3, vcc
	v_add_co_u32_e32 v14, vcc, s33, v2
	s_nop 1
	v_addc_co_u32_e32 v15, vcc, 0, v3, vcc
	v_add_co_u32_e32 v16, vcc, s34, v2
	s_nop 1
	v_addc_co_u32_e32 v17, vcc, 0, v3, vcc
	v_add_co_u32_e32 v18, vcc, s35, v2
	s_nop 1
	v_addc_co_u32_e32 v19, vcc, 0, v3, vcc
	v_add_co_u32_e32 v20, vcc, s36, v2
	flat_load_dword v34, v[4:5]
	flat_load_dword v69, v[2:3]
	flat_load_dword v68, v[6:7]
	flat_load_dword v67, v[8:9]
	flat_load_dword v66, v[10:11]
	flat_load_dword v55, v[12:13]
	flat_load_dword v54, v[14:15]
	flat_load_dword v53, v[16:17]
	flat_load_dword v52, v[18:19]
	v_addc_co_u32_e32 v21, vcc, 0, v3, vcc
	v_add_co_u32_e32 v22, vcc, s37, v2
	global_load_dwordx4 v[78:81], v35, s[22:23] offset:16
	global_load_dwordx4 v[82:85], v35, s[22:23]
	global_load_dwordx4 v[86:89], v35, s[22:23] offset:80
	global_load_dwordx4 v[90:93], v35, s[22:23] offset:64
	v_addc_co_u32_e32 v23, vcc, 0, v3, vcc
	v_add_co_u32_e32 v24, vcc, s38, v2
	v_lshl_add_u64 v[18:19], s[24:25], 0, v[46:47]
	s_nop 0
	v_addc_co_u32_e32 v25, vcc, 0, v3, vcc
	v_add_co_u32_e32 v26, vcc, s39, v2
	v_lshl_add_u64 v[18:19], v[18:19], 0, v[48:49]
	s_nop 0
	v_addc_co_u32_e32 v27, vcc, 0, v3, vcc
	v_add_co_u32_e32 v4, vcc, s40, v2
	v_lshl_add_u64 v[30:31], v[18:19], 0, s[12:13]
	s_nop 0
	v_addc_co_u32_e32 v5, vcc, 0, v3, vcc
	v_add_co_u32_e32 v6, vcc, s41, v2
	s_waitcnt vmcnt(0) lgkmcnt(0)
	v_fma_f32 v82, v69, v82, v34
	v_addc_co_u32_e32 v7, vcc, 0, v3, vcc
	global_load_dwordx4 v[94:97], v35, s[22:23] offset:48
	global_load_dwordx4 v[98:101], v35, s[22:23] offset:32
	global_load_dwordx4 v[102:105], v35, s[22:23] offset:112
	global_load_dwordx4 v[106:109], v35, s[22:23] offset:96
	flat_load_dword v77, v[20:21]
	flat_load_dword v76, v[22:23]
	flat_load_dword v74, v[24:25]
	flat_load_dword v72, v[26:27]
	flat_load_dword v71, v[4:5]
	flat_load_dword v70, v[6:7]
	v_add_co_u32_e32 v4, vcc, s42, v2
	v_fmac_f32_e32 v82, v68, v83
	s_nop 0
	v_addc_co_u32_e32 v5, vcc, 0, v3, vcc
	v_add_co_u32_e32 v2, vcc, s43, v2
	v_fmac_f32_e32 v82, v67, v84
	s_nop 0
	v_addc_co_u32_e32 v3, vcc, 0, v3, vcc
	flat_load_dword v75, v[4:5]
	flat_load_dword v73, v[2:3]
	v_or_b32_e32 v2, s4, v130
	v_mad_u64_u32 v[2:3], s[52:53], v2, s7, v[42:43]
	v_mad_i32_i24 v3, s5, v60, v3
	v_lshl_add_u64 v[2:3], v[2:3], 0, s[10:11]
	v_lshl_add_u64 v[50:51], v[2:3], 0, v[44:45]
	global_load_dwordx4 v[6:9], v[50:51], off offset:16
	global_load_dwordx4 v[14:17], v[50:51], off
	global_load_dwordx4 v[2:5], v[50:51], off offset:2064
	global_load_dwordx4 v[10:13], v[50:51], off offset:2048
	global_load_dwordx4 v[110:113], v35, s[22:23] offset:144
	global_load_dwordx4 v[114:117], v35, s[22:23] offset:128
	v_add_co_u32_e32 v18, vcc, s30, v18
	v_fmac_f32_e32 v82, v66, v85
	s_nop 0
	v_addc_co_u32_e32 v19, vcc, 0, v19, vcc
	global_load_dwordx4 v[22:25], v[18:19], off
	s_nop 0
	global_load_dwordx4 v[18:21], v[30:31], off offset:48
	global_load_dwordx4 v[118:121], v35, s[22:23] offset:176
	global_load_dwordx4 v[122:125], v35, s[22:23] offset:160
	global_load_dwordx4 v[26:29], v[30:31], off offset:32
	s_nop 0
	global_load_dwordx4 v[30:33], v[30:31], off offset:16
	s_nop 0
	global_load_dwordx4 v[126:129], v35, s[22:23] offset:240
	global_load_dwordx4 v[132:135], v35, s[22:23] offset:224
	global_load_dwordx4 v[136:139], v35, s[22:23] offset:208
	global_load_dwordx4 v[140:143], v35, s[22:23] offset:192
	v_fmac_f32_e32 v82, v55, v78
	v_fmac_f32_e32 v82, v54, v79
	v_fmac_f32_e32 v82, v53, v80
	v_fmac_f32_e32 v82, v52, v81
	v_fma_f32 v90, v69, v90, v34
	v_fmac_f32_e32 v90, v68, v91
	v_fmac_f32_e32 v90, v67, v92
	v_fmac_f32_e32 v90, v66, v93
	v_fmac_f32_e32 v90, v55, v86
	v_fmac_f32_e32 v90, v54, v87
	v_fmac_f32_e32 v90, v53, v88
	v_fmac_f32_e32 v90, v52, v89
	s_waitcnt vmcnt(0) lgkmcnt(0)
; __device__ __forceinline__ float prep_b(LAS unsigned char* lds, const float* glow_rows, const float (&wg)[16], float bg, int k, int seg, float (&bv)[16]) {
;     ...
;     for (int j = 0; j < 16; ++j) { const float* gl = glow_rows + (16 * seg + j) * 16; float z = bg;
; #pragma unroll
;         for (int r = 0; r < 16; ++r) z += gl[r] * wg[r];
;         const float ls = fminf(z, 0.f) - __logf(1.0f + __expf(-fabsf(z)));
;         cum += ls * (1.0f / 16.0f); bv[j] = cum; }
	v_fmac_f32_e32 v82, v77, v98
	v_fmac_f32_e32 v82, v76, v99
	v_fmac_f32_e32 v82, v74, v100
	v_fmac_f32_e32 v82, v72, v101
	v_fmac_f32_e32 v82, v71, v94
	v_fmac_f32_e32 v82, v70, v95
	v_fmac_f32_e32 v90, v77, v106
	v_fmac_f32_e32 v90, v76, v107
	v_fmac_f32_e32 v90, v74, v108
	v_fmac_f32_e32 v90, v72, v109
	v_fmac_f32_e32 v90, v71, v102
	v_fmac_f32_e32 v90, v70, v103
	v_fmac_f32_e32 v82, v75, v96
	v_fmac_f32_e32 v82, v73, v97
	v_mul_f32_e64 v78, |v82|, s44
	v_exp_f32_e32 v78, v78
	v_min_f32_e32 v79, 0, v82
	v_fmac_f32_e32 v90, v75, v104
	v_fmac_f32_e32 v90, v73, v105
	v_add_f32_e32 v78, 1.0, v78
	v_cmp_gt_f32_e32 vcc, s45, v78
	v_fma_f32 v98, v69, v114, v34
	v_fmac_f32_e32 v98, v68, v115
	v_cndmask_b32_e64 v80, 0, 32, vcc
	v_ldexp_f32 v78, v78, v80
	v_log_f32_e32 v78, v78
	v_cndmask_b32_e32 v81, 0, v61, vcc
	v_fmac_f32_e32 v98, v67, v116
	v_mul_f32_e64 v80, |v90|, s44
	v_mul_f32_e32 v82, 0x3f317217, v78
	v_fma_f32 v82, v78, s46, -v82
	v_fmac_f32_e32 v82, 0x3377d1cf, v78
	v_fmac_f32_e32 v82, 0x3f317217, v78
	v_cmp_lt_f32_e64 vcc, |v78|, s47
	v_fmac_f32_e32 v98, v66, v117
	v_exp_f32_e32 v80, v80
	v_cndmask_b32_e32 v78, v78, v82, vcc
	global_load_dwordx4 v[82:85], v35, s[22:23] offset:272
	global_load_dwordx4 v[86:89], v35, s[22:23] offset:256
	v_fmac_f32_e32 v98, v55, v110
	v_fmac_f32_e32 v98, v54, v111
	v_fmac_f32_e32 v98, v53, v112
	v_fmac_f32_e32 v98, v52, v113
	v_add_f32_e32 v80, 1.0, v80
	v_fmac_f32_e32 v98, v77, v122
	v_cmp_gt_f32_e32 vcc, s45, v80
	v_fmac_f32_e32 v98, v76, v123
	v_sub_f32_e32 v78, v78, v81
	v_cndmask_b32_e64 v81, 0, 32, vcc
	v_fmac_f32_e32 v98, v74, v124
	v_ldexp_f32 v80, v80, v81
	v_fmac_f32_e32 v98, v72, v125
	v_log_f32_e32 v80, v80
	v_sub_f32_e32 v78, v79, v78
	v_min_f32_e32 v79, 0, v90
	global_load_dwordx4 v[90:93], v35, s[22:23] offset:304
	global_load_dwordx4 v[94:97], v35, s[22:23] offset:288
	v_fmac_f32_e32 v98, v71, v118
	v_fmac_f32_e32 v98, v70, v119
	v_fmac_f32_e32 v98, v75, v120
	v_fmac_f32_e32 v98, v73, v121
	v_mul_f32_e32 v81, 0x3f317217, v80
	v_mul_f32_e64 v99, |v98|, s44
	v_fma_f32 v81, v80, s46, -v81
	v_exp_f32_e32 v99, v99
	v_fmac_f32_e32 v81, 0x3377d1cf, v80
	v_fmac_f32_e32 v81, 0x3f317217, v80
	v_cmp_lt_f32_e64 s[4:5], |v80|, s47
	v_fma_f32 v115, v69, v140, v34
	v_fmac_f32_e32 v115, v68, v141
	v_cndmask_b32_e64 v80, v80, v81, s[4:5]
	v_cndmask_b32_e32 v81, 0, v61, vcc
	v_sub_f32_e32 v80, v80, v81
	v_add_f32_e32 v81, 1.0, v99
	v_cmp_gt_f32_e32 vcc, s45, v81
	v_sub_f32_e32 v79, v79, v80
	v_min_f32_e32 v80, 0, v98
	v_cndmask_b32_e64 v99, 0, 32, vcc
	v_ldexp_f32 v81, v81, v99
	global_load_dwordx4 v[98:101], v35, s[22:23] offset:336
	global_load_dwordx4 v[102:105], v35, s[22:23] offset:320
	v_log_f32_e32 v81, v81
	v_fmac_f32_e32 v115, v67, v142
	v_fmac_f32_e32 v115, v66, v143
	v_fmac_f32_e32 v115, v55, v136
	v_mul_f32_e32 v106, 0x3f317217, v81
	v_fmac_f32_e32 v115, v54, v137
	v_fma_f32 v114, v81, s46, -v106
	global_load_dwordx4 v[106:109], v35, s[22:23] offset:368
	global_load_dwordx4 v[110:113], v35, s[22:23] offset:352
	v_fmac_f32_e32 v115, v53, v138
	v_fmac_f32_e32 v115, v52, v139
	v_fmac_f32_e32 v115, v77, v132
	v_fmac_f32_e32 v115, v76, v133
	v_fmac_f32_e32 v115, v74, v134
	v_fmac_f32_e32 v115, v72, v135
	v_fmac_f32_e32 v115, v71, v126
	v_fmac_f32_e32 v115, v70, v127
	v_fmac_f32_e32 v115, v75, v128
	v_fmac_f32_e32 v115, v73, v129
	v_mul_f32_e64 v116, |v115|, s44
	v_exp_f32_e32 v116, v116
	v_fmac_f32_e32 v114, 0x3377d1cf, v81
	v_fmac_f32_e32 v114, 0x3f317217, v81
	v_cmp_lt_f32_e64 s[4:5], |v81|, s47
	v_fma_f32 v78, v78, s48, 0
	v_fmamk_f32 v79, v79, 0x3d800000, v78
	v_cndmask_b32_e64 v81, v81, v114, s[4:5]
	v_cndmask_b32_e32 v114, 0, v61, vcc
	v_sub_f32_e32 v81, v81, v114
	v_add_f32_e32 v114, 1.0, v116
	v_cmp_gt_f32_e32 vcc, s45, v114
	v_sub_f32_e32 v80, v80, v81
	v_min_f32_e32 v81, 0, v115
	v_cndmask_b32_e64 v116, 0, 32, vcc
	v_ldexp_f32 v114, v114, v116
	v_log_f32_e32 v126, v114
	global_load_dwordx4 v[114:117], v35, s[22:23] offset:400
	global_load_dwordx4 v[118:121], v35, s[22:23] offset:384
	v_fmamk_f32 v80, v80, 0x3d800000, v79
	v_mul_f32_e32 v122, 0x3f317217, v126
	s_waitcnt vmcnt(8)
	v_fma_f32 v128, v69, v86, v34
	v_fmac_f32_e32 v128, v68, v87
	v_fmac_f32_e32 v128, v67, v88
	v_fma_f32 v127, v126, s46, -v122
	v_fmac_f32_e32 v128, v66, v89
	global_load_dwordx4 v[86:89], v35, s[22:23] offset:432
	global_load_dwordx4 v[122:125], v35, s[22:23] offset:416
	v_fmac_f32_e32 v128, v55, v82
	v_fmac_f32_e32 v128, v54, v83
	v_fmac_f32_e32 v128, v53, v84
	v_fmac_f32_e32 v128, v52, v85
	v_fmac_f32_e32 v127, 0x3377d1cf, v126
	v_fmac_f32_e32 v127, 0x3f317217, v126
	v_cmp_lt_f32_e64 s[4:5], |v126|, s47
	v_cndmask_b32_e32 v84, 0, v61, vcc
	s_waitcnt vmcnt(8)
	v_fmac_f32_e32 v128, v77, v94
	v_fmac_f32_e32 v128, v76, v95
	v_fmac_f32_e32 v128, v74, v96
	v_fmac_f32_e32 v128, v72, v97
	v_fmac_f32_e32 v128, v71, v90
	v_fmac_f32_e32 v128, v70, v91
	v_fmac_f32_e32 v128, v75, v92
	v_fmac_f32_e32 v128, v73, v93
	global_load_dwordx4 v[90:93], v35, s[22:23] offset:464
	global_load_dwordx4 v[94:97], v35, s[22:23] offset:448
	v_cndmask_b32_e64 v83, v126, v127, s[4:5]
	v_sub_f32_e32 v83, v83, v84
	v_mul_f32_e64 v82, |v128|, s44
	v_sub_f32_e32 v81, v81, v83
	v_min_f32_e32 v83, 0, v128
	v_exp_f32_e32 v82, v82
	v_fmamk_f32 v81, v81, 0x3d800000, v80
	v_add_f32_e32 v82, 1.0, v82
	v_cmp_gt_f32_e32 vcc, s45, v82
	s_waitcnt vmcnt(8)
	v_fma_f32 v85, v69, v102, v34
	v_fmac_f32_e32 v85, v68, v103
	v_fmac_f32_e32 v85, v67, v104
	v_fmac_f32_e32 v85, v66, v105
	global_load_dwordx4 v[102:105], v35, s[22:23] offset:496
	global_load_dwordx4 v[126:129], v35, s[22:23] offset:480
	v_fmac_f32_e32 v85, v55, v98
	v_fmac_f32_e32 v85, v54, v99
	v_fmac_f32_e32 v85, v53, v100
	v_fmac_f32_e32 v85, v52, v101
	s_waitcnt vmcnt(8)
; __device__ __forceinline__ float prep_b(LAS unsigned char* lds, const float* glow_rows, const float (&wg)[16], float bg, int k, int seg, float (&bv)[16]) {
;     ...
;     for (int j = 0; j < 16; ++j) { const float* gl = glow_rows + (16 * seg + j) * 16; float z = bg;
; #pragma unroll
;         for (int r = 0; r < 16; ++r) z += gl[r] * wg[r];
;         const float ls = fminf(z, 0.f) - __logf(1.0f + __expf(-fabsf(z)));
;         cum += ls * (1.0f / 16.0f); bv[j] = cum; }
	v_fmac_f32_e32 v85, v77, v110
	v_fmac_f32_e32 v85, v76, v111
	v_cndmask_b32_e64 v84, 0, 32, vcc
	v_fmac_f32_e32 v85, v74, v112
	v_ldexp_f32 v82, v82, v84
	v_fmac_f32_e32 v85, v72, v113
	v_log_f32_e32 v82, v82
	v_fmac_f32_e32 v85, v71, v106
	v_fmac_f32_e32 v85, v70, v107
	v_fmac_f32_e32 v85, v75, v108
	v_fmac_f32_e32 v85, v73, v109
	v_mul_f32_e32 v84, 0x3f317217, v82
	v_mul_f32_e64 v98, |v85|, s44
	v_fma_f32 v84, v82, s46, -v84
	v_exp_f32_e32 v98, v98
	v_fmac_f32_e32 v84, 0x3377d1cf, v82
	v_fmac_f32_e32 v84, 0x3f317217, v82
	v_cmp_lt_f32_e64 s[4:5], |v82|, s47
	s_waitcnt vmcnt(6)
	v_fma_f32 v131, v69, v118, v34
	v_cndmask_b32_e64 v82, v82, v84, s[4:5]
	v_cndmask_b32_e32 v84, 0, v61, vcc
	v_sub_f32_e32 v82, v82, v84
	v_add_f32_e32 v84, 1.0, v98
	v_cmp_gt_f32_e32 vcc, s45, v84
	v_fmac_f32_e32 v131, v68, v119
	v_fmac_f32_e32 v131, v67, v120
	v_cndmask_b32_e64 v98, 0, 32, vcc
	v_ldexp_f32 v84, v84, v98
	global_load_dwordx4 v[98:101], v35, s[22:23] offset:528
	global_load_dwordx4 v[106:109], v35, s[22:23] offset:512
	v_fmac_f32_e32 v131, v66, v121
	v_fmac_f32_e32 v131, v55, v114
	global_load_dwordx4 v[110:113], v35, s[22:23] offset:560
	global_load_dwordx4 v[118:121], v35, s[22:23] offset:544
	v_fmac_f32_e32 v131, v54, v115
	v_fmac_f32_e32 v131, v53, v116
	v_fmac_f32_e32 v131, v52, v117
	s_waitcnt vmcnt(8)
	v_fmac_f32_e32 v131, v77, v122
	v_fmac_f32_e32 v131, v76, v123
	v_fmac_f32_e32 v131, v74, v124
	v_fmac_f32_e32 v131, v72, v125
	v_log_f32_e32 v84, v84
	v_fmac_f32_e32 v131, v71, v86
	v_fmac_f32_e32 v131, v70, v87
	v_fmac_f32_e32 v131, v75, v88
	v_fmac_f32_e32 v131, v73, v89
	v_sub_f32_e32 v82, v83, v82
	v_min_f32_e32 v83, 0, v85
	v_mul_f32_e32 v85, 0x3f317217, v84
	v_mul_f32_e64 v86, |v131|, s44
	v_fma_f32 v85, v84, s46, -v85
	v_exp_f32_e32 v86, v86
	v_fmac_f32_e32 v85, 0x3377d1cf, v84
	v_fmac_f32_e32 v85, 0x3f317217, v84
	v_cmp_lt_f32_e64 s[4:5], |v84|, s47
	s_waitcnt vmcnt(6)
	v_fma_f32 v132, v69, v94, v34
	v_fmac_f32_e32 v132, v68, v95
	v_cndmask_b32_e64 v84, v84, v85, s[4:5]
	v_cndmask_b32_e32 v85, 0, v61, vcc
	v_sub_f32_e32 v84, v84, v85
	v_add_f32_e32 v85, 1.0, v86
	v_cmp_gt_f32_e32 vcc, s45, v85
	v_fmac_f32_e32 v132, v67, v96
	v_fmac_f32_e32 v132, v66, v97
	v_cndmask_b32_e64 v86, 0, 32, vcc
	v_ldexp_f32 v85, v85, v86
	global_load_dwordx4 v[86:89], v35, s[22:23] offset:592
	global_load_dwordx4 v[114:117], v35, s[22:23] offset:576
	v_fmac_f32_e32 v132, v55, v90
	v_fmac_f32_e32 v132, v54, v91
	v_log_f32_e32 v85, v85
	v_fmac_f32_e32 v132, v53, v92
	v_fmac_f32_e32 v132, v52, v93
	s_waitcnt vmcnt(6)
	v_fmac_f32_e32 v132, v77, v126
	v_fmac_f32_e32 v132, v76, v127
	v_mul_f32_e32 v122, 0x3f317217, v85
	v_fmac_f32_e32 v132, v74, v128
	v_sub_f32_e32 v83, v83, v84
	v_min_f32_e32 v84, 0, v131
	v_fma_f32 v131, v85, s46, -v122
	global_load_dwordx4 v[94:97], v35, s[22:23] offset:624
	global_load_dwordx4 v[122:125], v35, s[22:23] offset:608
	v_fmac_f32_e32 v132, v72, v129
	v_fmac_f32_e32 v132, v71, v102
	v_fmac_f32_e32 v132, v70, v103
	v_fmac_f32_e32 v132, v75, v104
	v_fmac_f32_e32 v132, v73, v105
	v_mul_f32_e64 v90, |v132|, s44
	v_exp_f32_e32 v90, v90
	v_fmac_f32_e32 v131, 0x3377d1cf, v85
	v_fmac_f32_e32 v131, 0x3f317217, v85
	v_cmp_lt_f32_e64 s[4:5], |v85|, s47
	v_add_f32_e32 v90, 1.0, v90
	v_cndmask_b32_e32 v91, 0, v61, vcc
	v_cndmask_b32_e64 v85, v85, v131, s[4:5]
	v_cmp_gt_f32_e32 vcc, s45, v90
	v_sub_f32_e32 v85, v85, v91
	v_sub_f32_e32 v84, v84, v85
	v_cndmask_b32_e64 v91, 0, 32, vcc
	v_ldexp_f32 v90, v90, v91
	v_log_f32_e32 v131, v90
	global_load_dwordx4 v[90:93], v35, s[22:23] offset:656
	global_load_dwordx4 v[102:105], v35, s[22:23] offset:640
	v_min_f32_e32 v85, 0, v132
	v_fmamk_f32 v82, v82, 0x3d800000, v81
	v_mul_f32_e32 v126, 0x3f317217, v131
	v_fma_f32 v132, v131, s46, -v126
	v_fmac_f32_e32 v132, 0x3377d1cf, v131
	v_fmac_f32_e32 v132, 0x3f317217, v131
	v_cmp_lt_f32_e64 s[4:5], |v131|, s47
	v_fmamk_f32 v83, v83, 0x3d800000, v82
	v_fmamk_f32 v84, v84, 0x3d800000, v83
	s_waitcnt vmcnt(8)
	v_fma_f32 v133, v69, v106, v34
	v_fmac_f32_e32 v133, v68, v107
	v_fmac_f32_e32 v133, v67, v108
	v_fmac_f32_e32 v133, v66, v109
	v_fmac_f32_e32 v133, v55, v98
	v_fmac_f32_e32 v133, v54, v99
	v_fmac_f32_e32 v133, v53, v100
	global_load_dwordx4 v[106:109], v35, s[22:23] offset:688
	global_load_dwordx4 v[126:129], v35, s[22:23] offset:672
	v_fmac_f32_e32 v133, v52, v101
	s_waitcnt vmcnt(8)
	v_fmac_f32_e32 v133, v77, v118
	v_fmac_f32_e32 v133, v76, v119
	v_fmac_f32_e32 v133, v74, v120
	v_fmac_f32_e32 v133, v72, v121
	v_fmac_f32_e32 v133, v71, v110
	v_fmac_f32_e32 v133, v70, v111
	v_fmac_f32_e32 v133, v75, v112
	v_fmac_f32_e32 v133, v73, v113
	v_mul_f32_e64 v98, |v133|, s44
	v_exp_f32_e32 v98, v98
	v_cndmask_b32_e64 v99, v131, v132, s[4:5]
	v_cndmask_b32_e32 v100, 0, v61, vcc
	v_sub_f32_e32 v99, v99, v100
	v_add_f32_e32 v98, 1.0, v98
	v_cmp_gt_f32_e32 vcc, s45, v98
	v_sub_f32_e32 v85, v85, v99
	v_min_f32_e32 v132, 0, v133
	v_cndmask_b32_e64 v100, 0, 32, vcc
	v_ldexp_f32 v98, v98, v100
	v_log_f32_e32 v131, v98
	v_fmamk_f32 v85, v85, 0x3d800000, v84
	v_mul_f32_e32 v98, 0x3f317217, v131
	v_fma_f32 v133, v131, s46, -v98
	global_load_dwordx4 v[98:101], v35, s[22:23] offset:720
	global_load_dwordx4 v[110:113], v35, s[22:23] offset:704
	v_fmac_f32_e32 v133, 0x3377d1cf, v131
	s_waitcnt vmcnt(8)
	v_fma_f32 v134, v69, v114, v34
	v_fmac_f32_e32 v134, v68, v115
	v_fmac_f32_e32 v134, v67, v116
	v_fmac_f32_e32 v134, v66, v117
	v_fmac_f32_e32 v134, v55, v86
	v_fmac_f32_e32 v134, v54, v87
	v_fmac_f32_e32 v134, v53, v88
	v_fmac_f32_e32 v134, v52, v89
	global_load_dwordx4 v[114:117], v35, s[22:23] offset:752
	global_load_dwordx4 v[118:121], v35, s[22:23] offset:736
	v_fmac_f32_e32 v133, 0x3f317217, v131
	v_cmp_lt_f32_e64 s[4:5], |v131|, s47
	v_cndmask_b32_e32 v88, 0, v61, vcc
	s_waitcnt vmcnt(8)
; __device__ __forceinline__ float prep_b(LAS unsigned char* lds, const float* glow_rows, const float (&wg)[16], float bg, int k, int seg, float (&bv)[16]) {
;     ...
;     for (int j = 0; j < 16; ++j) { const float* gl = glow_rows + (16 * seg + j) * 16; float z = bg;
; #pragma unroll
;         for (int r = 0; r < 16; ++r) z += gl[r] * wg[r];
;         const float ls = fminf(z, 0.f) - __logf(1.0f + __expf(-fabsf(z)));
;         cum += ls * (1.0f / 16.0f); bv[j] = cum; }
	v_fmac_f32_e32 v134, v77, v122
	v_fmac_f32_e32 v134, v76, v123
	v_fmac_f32_e32 v134, v74, v124
	v_fmac_f32_e32 v134, v72, v125
	v_fmac_f32_e32 v134, v71, v94
	v_fmac_f32_e32 v134, v70, v95
	v_fmac_f32_e32 v134, v75, v96
	v_fmac_f32_e32 v134, v73, v97
	v_mul_f32_e64 v86, |v134|, s44
	v_exp_f32_e32 v86, v86
	global_load_dwordx4 v[94:97], v35, s[22:23] offset:784
	global_load_dwordx4 v[122:125], v35, s[22:23] offset:768
	v_cndmask_b32_e64 v87, v131, v133, s[4:5]
	v_sub_f32_e32 v87, v87, v88
	v_add_f32_e32 v86, 1.0, v86
	v_cmp_gt_f32_e32 vcc, s45, v86
	s_waitcnt vmcnt(8)
	v_fma_f32 v131, v69, v102, v34
	v_cndmask_b32_e64 v88, 0, 32, vcc
	v_fmac_f32_e32 v131, v68, v103
	v_ldexp_f32 v86, v86, v88
	v_fmac_f32_e32 v131, v67, v104
	v_log_f32_e32 v88, v86
	v_sub_f32_e32 v86, v132, v87
	v_min_f32_e32 v87, 0, v134
	v_fmac_f32_e32 v131, v66, v105
	global_load_dwordx4 v[102:105], v35, s[22:23] offset:816
	global_load_dwordx4 v[132:135], v35, s[22:23] offset:800
	v_fmac_f32_e32 v131, v55, v90
	v_fmac_f32_e32 v131, v54, v91
	v_fmac_f32_e32 v131, v53, v92
	v_fmac_f32_e32 v131, v52, v93
	v_mul_f32_e32 v89, 0x3f317217, v88
	v_fma_f32 v89, v88, s46, -v89
	v_fmac_f32_e32 v89, 0x3377d1cf, v88
	v_fmac_f32_e32 v89, 0x3f317217, v88
	s_waitcnt vmcnt(8)
	v_fmac_f32_e32 v131, v77, v126
	v_fmac_f32_e32 v131, v76, v127
	v_fmac_f32_e32 v131, v74, v128
	v_fmac_f32_e32 v131, v72, v129
	v_fmac_f32_e32 v131, v71, v106
	v_fmac_f32_e32 v131, v70, v107
	v_fmac_f32_e32 v131, v75, v108
	v_fmac_f32_e32 v131, v73, v109
	v_mul_f32_e64 v90, |v131|, s44
	v_exp_f32_e32 v90, v90
	v_cmp_lt_f32_e64 s[4:5], |v88|, s47
	v_fmamk_f32 v86, v86, 0x3d800000, v85
	s_waitcnt vmcnt(6)
	v_fma_f32 v140, v69, v110, v34
	v_cndmask_b32_e64 v88, v88, v89, s[4:5]
	v_cndmask_b32_e32 v89, 0, v61, vcc
	v_sub_f32_e32 v88, v88, v89
	v_add_f32_e32 v89, 1.0, v90
	v_cmp_gt_f32_e32 vcc, s45, v89
	v_fmac_f32_e32 v140, v68, v111
	v_fmac_f32_e32 v140, v67, v112
	v_cndmask_b32_e64 v90, 0, 32, vcc
	v_ldexp_f32 v89, v89, v90
	v_log_f32_e32 v89, v89
	v_fmac_f32_e32 v140, v66, v113
	v_fmac_f32_e32 v140, v55, v98
	v_fmac_f32_e32 v140, v54, v99
	v_mul_f32_e32 v90, 0x3f317217, v89
	v_fma_f32 v126, v89, s46, -v90
	global_load_dwordx4 v[90:93], v35, s[22:23] offset:848
	global_load_dwordx4 v[106:109], v35, s[22:23] offset:832
	v_fmac_f32_e32 v126, 0x3377d1cf, v89
	v_fmac_f32_e32 v126, 0x3f317217, v89
	v_cmp_lt_f32_e64 s[4:5], |v89|, s47
	v_fmac_f32_e32 v140, v53, v100
	v_fmac_f32_e32 v140, v52, v101
	v_cndmask_b32_e64 v89, v89, v126, s[4:5]
	global_load_dwordx4 v[126:129], v35, s[22:23] offset:880
	global_load_dwordx4 v[136:139], v35, s[22:23] offset:864
	s_waitcnt vmcnt(8)
	v_fmac_f32_e32 v140, v77, v118
	v_fmac_f32_e32 v140, v76, v119
	v_fmac_f32_e32 v140, v74, v120
	v_fmac_f32_e32 v140, v72, v121
	v_fmac_f32_e32 v140, v71, v114
	v_fmac_f32_e32 v140, v70, v115
	v_fmac_f32_e32 v140, v75, v116
	s_waitcnt vmcnt(6)
	v_fma_f32 v122, v69, v122, v34
	v_fmac_f32_e32 v140, v73, v117
	v_fmac_f32_e32 v122, v68, v123
	v_mul_f32_e64 v98, |v140|, s44
	v_fmac_f32_e32 v122, v67, v124
	v_exp_f32_e32 v98, v98
	v_fmac_f32_e32 v122, v66, v125
	v_fmac_f32_e32 v122, v55, v94
	v_sub_f32_e32 v87, v87, v88
	v_min_f32_e32 v88, 0, v131
	v_cndmask_b32_e32 v131, 0, v61, vcc
	v_fmac_f32_e32 v122, v54, v95
	v_sub_f32_e32 v89, v89, v131
	v_fmac_f32_e32 v122, v53, v96
	v_sub_f32_e32 v88, v88, v89
	v_add_f32_e32 v89, 1.0, v98
	v_fmac_f32_e32 v122, v52, v97
	v_cmp_gt_f32_e32 vcc, s45, v89
	s_waitcnt vmcnt(4)
	v_fmac_f32_e32 v122, v77, v132
	v_fmac_f32_e32 v122, v76, v133
	v_cndmask_b32_e64 v98, 0, 32, vcc
	v_ldexp_f32 v89, v89, v98
	global_load_dwordx4 v[98:101], v35, s[22:23] offset:912
	global_load_dwordx4 v[110:113], v35, s[22:23] offset:896
	v_fmac_f32_e32 v122, v74, v134
	v_fmac_f32_e32 v122, v72, v135
	v_log_f32_e32 v89, v89
	v_fmac_f32_e32 v122, v71, v102
	v_fmac_f32_e32 v122, v70, v103
	v_fmac_f32_e32 v122, v75, v104
	v_fmac_f32_e32 v122, v73, v105
	v_mul_f32_e32 v114, 0x3f317217, v89
	v_mul_f32_e64 v94, |v122|, s44
	v_min_f32_e32 v131, 0, v140
	v_fma_f32 v140, v89, s46, -v114
	v_exp_f32_e32 v94, v94
	v_fmac_f32_e32 v140, 0x3377d1cf, v89
	global_load_dwordx4 v[114:117], v35, s[22:23] offset:944
	global_load_dwordx4 v[118:121], v35, s[22:23] offset:928
	v_fmac_f32_e32 v140, 0x3f317217, v89
	v_cmp_lt_f32_e64 s[4:5], |v89|, s47
	v_cndmask_b32_e32 v95, 0, v61, vcc
	v_add_f32_e32 v123, 1.0, v94
	v_cndmask_b32_e64 v89, v89, v140, s[4:5]
	v_sub_f32_e32 v89, v89, v95
	global_load_dwordx4 v[94:97], v35, s[22:23] offset:976
	global_load_dwordx4 v[102:105], v35, s[22:23] offset:960
	v_cmp_gt_f32_e32 vcc, s45, v123
	v_sub_f32_e32 v89, v131, v89
	v_min_f32_e32 v131, 0, v122
	v_cndmask_b32_e64 v124, 0, 32, vcc
	v_ldexp_f32 v123, v123, v124
	v_log_f32_e32 v140, v123
	global_load_dwordx4 v[122:125], v35, s[22:23] offset:1008
	global_load_dwordx4 v[132:135], v35, s[22:23] offset:992
	v_fmamk_f32 v87, v87, 0x3d800000, v86
	v_fmamk_f32 v88, v88, 0x3d800000, v87
	v_mul_f32_e32 v141, 0x3f317217, v140
	v_fma_f32 v141, v140, s46, -v141
	v_fmac_f32_e32 v141, 0x3377d1cf, v140
	v_fmac_f32_e32 v141, 0x3f317217, v140
	v_cmp_lt_f32_e64 s[4:5], |v140|, s47
	v_fmamk_f32 v89, v89, 0x3d800000, v88
	s_waitcnt vmcnt(10)
; #define LAS __attribute__((address_space(3)))
; __device__ __forceinline__ float prep_b(LAS unsigned char* lds, const float* glow_rows, const float (&wg)[16], float bg, int k, int seg, float (&bv)[16]) {
;     ...
;     for (int j = 0; j < 16; ++j) { const float* gl = glow_rows + (16 * seg + j) * 16; float z = bg;
; #pragma unroll
;         for (int r = 0; r < 16; ++r) z += gl[r] * wg[r];
;         const float ls = fminf(z, 0.f) - __logf(1.0f + __expf(-fabsf(z)));
;         cum += ls * (1.0f / 16.0f); bv[j] = cum; }
;     LAS float* SEG = (LAS float*)(lds + L_SEG);
;     SEG[seg * 128 + k] = cum;
;     __syncthreads();
;     float pre = 0.f, tot = 0.f;
; #pragma unroll
;     for (int s2 = 0; s2 < 4; ++s2) { const float v = SEG[s2 * 128 + k]; tot += v; pre += (s2 < seg) ? v : 0.f; }
; #pragma unroll
;     for (int j = 0; j < 16; ++j) bv[j] += pre;
;     if (seg == 0) ((LAS float*)(lds + L_BT))[k] = __expf(tot);
	v_fma_f32 v106, v69, v106, v34
	v_fmac_f32_e32 v106, v68, v107
	v_fmac_f32_e32 v106, v67, v108
	v_fmac_f32_e32 v106, v66, v109
	v_fmac_f32_e32 v106, v55, v90
	v_fmac_f32_e32 v106, v54, v91
	v_fmac_f32_e32 v106, v53, v92
	v_fmac_f32_e32 v106, v52, v93
	s_waitcnt vmcnt(8)
	v_fmac_f32_e32 v106, v77, v136
	v_fmac_f32_e32 v106, v76, v137
	v_fmac_f32_e32 v106, v74, v138
	v_fmac_f32_e32 v106, v72, v139
	v_fmac_f32_e32 v106, v71, v126
	v_fmac_f32_e32 v106, v70, v127
	v_fmac_f32_e32 v106, v75, v128
	v_fmac_f32_e32 v106, v73, v129
	v_mul_f32_e64 v90, |v106|, s44
	v_exp_f32_e32 v90, v90
	v_cndmask_b32_e64 v91, v140, v141, s[4:5]
	v_cndmask_b32_e32 v92, 0, v61, vcc
	v_sub_f32_e32 v91, v91, v92
	v_add_f32_e32 v90, 1.0, v90
	v_cmp_gt_f32_e32 vcc, s45, v90
	s_nop 1
	v_cndmask_b32_e64 v92, 0, 32, vcc
	v_ldexp_f32 v90, v90, v92
	v_log_f32_e32 v92, v90
	v_sub_f32_e32 v90, v131, v91
	v_min_f32_e32 v91, 0, v106
	v_fmamk_f32 v90, v90, 0x3d800000, v89
	v_mul_f32_e32 v93, 0x3f317217, v92
	v_fma_f32 v93, v92, s46, -v93
	v_fmac_f32_e32 v93, 0x3377d1cf, v92
	v_fmac_f32_e32 v93, 0x3f317217, v92
	v_cmp_lt_f32_e64 s[4:5], |v92|, s47
	s_waitcnt vmcnt(6)
	v_fma_f32 v106, v69, v110, v34
	v_fmac_f32_e32 v106, v68, v111
	v_fmac_f32_e32 v106, v67, v112
	v_fmac_f32_e32 v106, v66, v113
	v_fmac_f32_e32 v106, v55, v98
	v_fmac_f32_e32 v106, v54, v99
	v_fmac_f32_e32 v106, v53, v100
	v_fmac_f32_e32 v106, v52, v101
	v_cndmask_b32_e64 v92, v92, v93, s[4:5]
	v_cndmask_b32_e32 v93, 0, v61, vcc
	v_sub_f32_e32 v92, v92, v93
	v_sub_f32_e32 v91, v91, v92
	v_fmamk_f32 v91, v91, 0x3d800000, v90
	s_waitcnt vmcnt(4)
	v_fmac_f32_e32 v106, v77, v118
	v_fmac_f32_e32 v106, v76, v119
	v_fmac_f32_e32 v106, v74, v120
	v_fmac_f32_e32 v106, v72, v121
	v_fmac_f32_e32 v106, v71, v114
	v_fmac_f32_e32 v106, v70, v115
	v_fmac_f32_e32 v106, v75, v116
	s_waitcnt vmcnt(2)
	v_fmac_f32_e32 v34, v69, v102
	v_fmac_f32_e32 v34, v68, v103
	v_fmac_f32_e32 v34, v67, v104
	v_fmac_f32_e32 v34, v66, v105
	v_fmac_f32_e32 v106, v73, v117
	v_fmac_f32_e32 v34, v55, v94
	v_mul_f32_e64 v98, |v106|, s44
	v_fmac_f32_e32 v34, v54, v95
	v_exp_f32_e32 v98, v98
	v_fmac_f32_e32 v34, v53, v96
	v_fmac_f32_e32 v34, v52, v97
	s_waitcnt vmcnt(0)
	v_fmac_f32_e32 v34, v77, v132
	v_fmac_f32_e32 v34, v76, v133
	v_add_f32_e32 v93, 1.0, v98
	v_fmac_f32_e32 v34, v74, v134
	v_cmp_gt_f32_e32 vcc, s45, v93
	v_fmac_f32_e32 v34, v72, v135
	v_fmac_f32_e32 v34, v71, v122
	v_cndmask_b32_e64 v98, 0, 32, vcc
	v_ldexp_f32 v93, v93, v98
	v_fmac_f32_e32 v34, v70, v123
	v_log_f32_e32 v93, v93
	v_fmac_f32_e32 v34, v75, v124
	v_fmac_f32_e32 v34, v73, v125
	v_mul_f32_e64 v52, |v34|, s44
	v_exp_f32_e32 v52, v52
	v_mul_f32_e32 v98, 0x3f317217, v93
	v_fma_f32 v98, v93, s46, -v98
	v_fmac_f32_e32 v98, 0x3377d1cf, v93
	v_fmac_f32_e32 v98, 0x3f317217, v93
	v_cmp_lt_f32_e64 s[4:5], |v93|, s47
	v_add_f32_e32 v52, 1.0, v52
	v_cndmask_b32_e32 v54, 0, v61, vcc
	v_cndmask_b32_e64 v53, v93, v98, s[4:5]
	v_cmp_gt_f32_e32 vcc, s45, v52
	v_sub_f32_e32 v53, v53, v54
	v_min_f32_e32 v92, 0, v106
	v_cndmask_b32_e64 v54, 0, 32, vcc
	v_ldexp_f32 v52, v52, v54
	v_log_f32_e32 v52, v52
	v_sub_f32_e32 v53, v92, v53
	v_fmamk_f32 v66, v53, 0x3d800000, v91
	v_min_f32_e32 v34, 0, v34
	v_mul_f32_e32 v53, 0x3f317217, v52
	v_fma_f32 v53, v52, s46, -v53
	v_fmac_f32_e32 v53, 0x3377d1cf, v52
	v_fmac_f32_e32 v53, 0x3f317217, v52
	v_cmp_lt_f32_e64 s[4:5], |v52|, s47
	s_nop 1
	v_cndmask_b32_e64 v52, v52, v53, s[4:5]
	v_cndmask_b32_e32 v53, 0, v61, vcc
	v_sub_f32_e32 v52, v52, v53
	v_sub_f32_e32 v34, v34, v52
	v_fmamk_f32 v67, v34, 0x3d800000, v66
	v_lshl_add_u32 v34, s50, 9, v57
	ds_write_b32 v34, v67
	s_waitcnt lgkmcnt(0)
	s_barrier
	ds_read2st64_b32 v[54:55], v57 offset1:2
	ds_read2st64_b32 v[52:53], v57 offset0:4 offset1:6
	s_cselect_b64 s[4:5], -1, 0
	s_cmpk_gt_u32 s49, 0x7f
	s_waitcnt lgkmcnt(1)
	v_add_f32_e32 v54, 0, v54
	v_add_f32_e32 v34, v54, v55
	s_waitcnt lgkmcnt(0)
	v_add_f32_e32 v34, v34, v52
	v_add_f32_e32 v34, v34, v53
	v_mul_f32_e32 v34, 0x3fb8aa3b, v34
	v_exp_f32_e32 v34, v34
	s_cbranch_scc1 .LBB0_626
	ds_write_b32 v57, v34 offset:2048

; #define LAS __attribute__((address_space(3)))
; __device__ __forceinline__ int crow(int r, int hi) { return (r & 3) + 8 * (r >> 2) + 4 * hi; }
; __device__ __forceinline__ int crow(int r, int hi) { return (r & 3) + 8 * (r >> 2) + 4 * hi; }
; __device__ __forceinline__ void gc_unit(LAS unsigned char* lds, int unit, const bf16_t* proj, const bf16_t* dSt, const float* gnorm, bf16_t* omix, int tid, int wave, int lane) {
;     ...
;       for (int ks = 0; ks < 8; ++ks) { const bf16x8 bb = sfr[ks];
;           const bf16x8 a0 = *(const LAS bf16x8*)(lds + L_QD + r * 272 + ks * 32 + hh * 16), a1 = *(const LAS bf16x8*)(lds + L_QD + (32 + r) * 272 + ks * 32 + hh * 16);
;           o0 = __builtin_amdgcn_mfma_f32_32x32x16_bf16(a0, bb, o0, 0, 0, 0); o1 = __builtin_amdgcn_mfma_f32_32x32x16_bf16(a1, bb, o1, 0, 0, 0); } }
;     __syncthreads();
; #pragma unroll
;     for (int i = 0; i < 16; ++i) { const int c = crow(i, hh); *(LAS float*)(lds + L_OT + c * 1040 + (32 * wave + r) * 4) = o0[i]; *(LAS float*)(lds + L_OT + (32 + c) * 1040 + (32 * wave + r) * 4) = o1[i]; }
;     ...
;         const u32x2 gw2 = *((const u32x2*)(proj + (row0 + c) * PROJ_LD + C_GOUT + h * 256) + lane);
.LBB0_1008:
	ds_read_b128 v[2:5], v105
	ds_read_b128 v[114:117], v105 offset:32
	ds_read_b128 v[22:25], v106
	ds_read_b128 v[118:121], v106 offset:32
	s_lshl_b32 s38, s38, 1
	s_add_u32 s50, s48, s33
	s_waitcnt lgkmcnt(3)
	v_mfma_f32_32x32x16_bf16 v[2:17], v[2:5], v[18:21], 0
	s_addc_u32 s51, s49, 0
	s_mul_i32 s40, s51, 0x3000
	s_mul_hi_u32 s41, s50, 0x3000
	s_add_i32 s41, s41, s40
	s_mul_i32 s40, s50, 0x3000
	s_add_u32 s40, s90, s40
	s_addc_u32 s41, s91, s41
	s_waitcnt lgkmcnt(1)
	v_mfma_f32_32x32x16_bf16 v[18:33], v[22:25], v[18:21], 0
	v_lshlrev_b32_e32 v78, 4, v182
	s_add_u32 s40, s40, s38
	s_addc_u32 s41, s41, 0
	v_lshlrev_b32_e32 v122, 3, v182
	v_add_u32_e32 v122, 0x2000, v122
	v_mov_b32_e32 v123, 0
	v_mov_b32_e32 v124, 0x3000
	v_mov_b32_e32 v125, 0
	v_lshl_add_u64 v[122:123], s[40:41], 0, v[122:123]
	global_load_dwordx2 v[126:127], v[122:123], off
	v_lshl_add_u64 v[122:123], v[122:123], 0, v[124:125]
	global_load_dwordx2 v[128:129], v[122:123], off
	v_lshl_add_u64 v[122:123], v[122:123], 0, v[124:125]
	global_load_dwordx2 v[130:131], v[122:123], off
	v_lshl_add_u64 v[122:123], v[122:123], 0, v[124:125]
	global_load_dwordx2 v[132:133], v[122:123], off
	v_lshl_add_u64 v[122:123], v[122:123], 0, v[124:125]
	global_load_dwordx2 v[134:135], v[122:123], off
	v_lshl_add_u64 v[122:123], v[122:123], 0, v[124:125]
	global_load_dwordx2 v[136:137], v[122:123], off
	v_lshl_add_u64 v[122:123], v[122:123], 0, v[124:125]
	global_load_dwordx2 v[138:139], v[122:123], off
	v_lshl_add_u64 v[122:123], v[122:123], 0, v[124:125]
	global_load_dwordx2 v[140:141], v[122:123], off
	v_lshl_add_u64 v[84:85], v[84:85], 0, s[44:45]
	v_mfma_f32_32x32x16_bf16 v[2:17], v[114:117], v[74:77], v[2:17]
	s_waitcnt lgkmcnt(0)
	v_mfma_f32_32x32x16_bf16 v[18:33], v[118:121], v[74:77], v[18:33]
	ds_read_b128 v[74:77], v105 offset:64
	ds_read_b128 v[114:117], v105 offset:96
	s_waitcnt lgkmcnt(1)
	v_mfma_f32_32x32x16_bf16 v[2:17], v[74:77], v[70:73], v[2:17]
	ds_read_b128 v[74:77], v106 offset:64
	ds_read_b128 v[118:121], v106 offset:96
	s_waitcnt lgkmcnt(1)
	v_mfma_f32_32x32x16_bf16 v[18:33], v[74:77], v[70:73], v[18:33]
	v_mfma_f32_32x32x16_bf16 v[2:17], v[114:117], v[66:69], v[2:17]
	s_waitcnt lgkmcnt(0)
	v_mfma_f32_32x32x16_bf16 v[18:33], v[118:121], v[66:69], v[18:33]
	ds_read_b128 v[66:69], v107 offset:4096
	ds_read_b128 v[70:73], v107 offset:4128
	s_waitcnt lgkmcnt(1)
	v_mfma_f32_32x32x16_bf16 v[2:17], v[66:69], v[38:41], v[2:17]
	ds_read_b128 v[66:69], v108 offset:4096
	ds_read_b128 v[74:77], v108 offset:4128
	s_waitcnt lgkmcnt(1)
	v_mfma_f32_32x32x16_bf16 v[18:33], v[66:69], v[38:41], v[18:33]
	v_mfma_f32_32x32x16_bf16 v[2:17], v[70:73], v[34:37], v[2:17]
	s_waitcnt lgkmcnt(0)
	v_mfma_f32_32x32x16_bf16 v[18:33], v[74:77], v[34:37], v[18:33]
	ds_read_b128 v[34:37], v107 offset:4160
	ds_read_b128 v[38:41], v107 offset:4192
	s_waitcnt lgkmcnt(1)
	v_mfma_f32_32x32x16_bf16 v[2:17], v[34:37], v[62:65], v[2:17]
	ds_read_b128 v[34:37], v108 offset:4160
	ds_read_b128 v[66:69], v108 offset:4192
	s_waitcnt lgkmcnt(1)
	v_mfma_f32_32x32x16_bf16 v[18:33], v[34:37], v[62:65], v[18:33]
	v_mfma_f32_32x32x16_bf16 v[2:17], v[38:41], v[58:61], v[2:17]
	ds_read_b128 v[34:37], v107 offset:4224
	ds_read_b128 v[38:41], v107 offset:4256
	s_waitcnt lgkmcnt(2)
	v_mfma_f32_32x32x16_bf16 v[18:33], v[66:69], v[58:61], v[18:33]
	s_waitcnt lgkmcnt(1)
	v_mfma_f32_32x32x16_bf16 v[2:17], v[34:37], v[54:57], v[2:17]
	ds_read_b128 v[34:37], v108 offset:4224
	ds_read_b128 v[58:61], v108 offset:4256
	s_waitcnt lgkmcnt(1)
	v_mfma_f32_32x32x16_bf16 v[18:33], v[34:37], v[54:57], v[18:33]
	v_mfma_f32_32x32x16_bf16 v[2:17], v[38:41], v[50:53], v[2:17]
	ds_read_b128 v[34:37], v107 offset:4288
	ds_read_b128 v[38:41], v107 offset:4320
	s_waitcnt lgkmcnt(2)
	v_mfma_f32_32x32x16_bf16 v[18:33], v[58:61], v[50:53], v[18:33]
	s_waitcnt lgkmcnt(1)
	v_mfma_f32_32x32x16_bf16 v[2:17], v[34:37], v[46:49], v[2:17]
	ds_read_b128 v[34:37], v108 offset:4288
	ds_read_b128 v[50:53], v108 offset:4320
	s_waitcnt lgkmcnt(0)
	s_barrier
	v_mfma_f32_32x32x16_bf16 v[18:33], v[34:37], v[46:49], v[18:33]
	v_mfma_f32_32x32x16_bf16 v[2:17], v[38:41], v[42:45], v[2:17]
	v_mfma_f32_32x32x16_bf16 v[18:33], v[50:53], v[42:45], v[18:33]
	s_nop 10
	ds_write_b32 v109, v2 offset:4096
	v_add_u32_e32 v2, s52, v98
	ds_write_b32 v109, v18 offset:37376
	ds_write_b32 v109, v3 offset:5136
	ds_write_b32 v109, v19 offset:38416
	ds_write_b32 v109, v4 offset:6176
	ds_write_b32 v109, v20 offset:39456
	ds_write_b32 v109, v5 offset:7216
	ds_write_b32 v109, v21 offset:40496
	ds_write_b32 v109, v6 offset:12416
	ds_write_b32 v109, v22 offset:45696
	ds_write_b32 v109, v7 offset:13456
	ds_write_b32 v109, v23 offset:46736
	ds_write_b32 v109, v8 offset:14496
	ds_write_b32 v109, v24 offset:47776
	ds_write_b32 v109, v9 offset:15536
	ds_write_b32 v109, v25 offset:48816
	ds_write_b32 v109, v10 offset:20736
	ds_write_b32 v109, v26 offset:54016
	ds_write_b32 v109, v11 offset:21776
	ds_write_b32 v109, v27 offset:55056
	ds_write_b32 v109, v12 offset:22816
	ds_write_b32 v109, v28 offset:56096
	ds_write_b32 v109, v13 offset:23856
	ds_write_b32 v109, v29 offset:57136
	ds_write_b32 v109, v14 offset:29056
	ds_write_b32 v109, v30 offset:62336
	ds_write_b32 v109, v15 offset:30096
	ds_write_b32 v109, v31 offset:63376
	ds_write_b32 v109, v16 offset:31136
	ds_write_b32 v109, v32 offset:64416
	ds_write_b32 v109, v17 offset:32176
	ds_write_b32 v109, v33 offset:65456
	s_waitcnt lgkmcnt(0)
	s_barrier
; #define LAS __attribute__((address_space(3)))
; __device__ __forceinline__ unsigned cvt_pk_bf16(float lo, float hi) { unsigned r; asm volatile("v_cvt_pk_bf16_f32 %0, %1, %2" : "=v"(r) : "v"(lo), "v"(hi)); return r; }
; __device__ __forceinline__ float bflo(unsigned w) { return __uint_as_float(w << 16); }
; __device__ __forceinline__ float bfhi(unsigned w) { return __uint_as_float(w & 0xffff0000u); }
; __device__ __forceinline__ void gc_unit(LAS unsigned char* lds, int unit, const bf16_t* proj, const bf16_t* dSt, const float* gnorm, bf16_t* omix, int tid, int wave, int lane) {
;     ...
;     const f32x4 g = *((const f32x4*)gnorm + lane);
; #pragma unroll
;     for (int rr = 0; rr < 8; ++rr) { const int c = 8 * wave + rr; const f32x4 v = *(const LAS f32x4*)(lds + L_OT + c * 1040 + lane * 16);
;         float ss = (v[0] * v[0] + v[1] * v[1]) + (v[2] * v[2] + v[3] * v[3]);
; #pragma unroll
;         for (int o = 1; o < 64; o <<= 1) ss += __shfl_xor(ss, o);
;         const float rs = 1.0f / sqrtf(ss * (1.0f / 256.0f) + EPS);
;         const u32x2 gw2 = *((const u32x2*)(proj + (row0 + c) * PROJ_LD + C_GOUT + h * 256) + lane);
;         const float z0 = bflo(gw2.x), z1 = bfhi(gw2.x), z2 = bflo(gw2.y), z3 = bfhi(gw2.y);
;         const float p0 = v[0] * rs * g[0] * (z0 / (1.0f + __expf(-z0))), p1 = v[1] * rs * g[1] * (z1 / (1.0f + __expf(-z1)));
;         const float p2 = v[2] * rs * g[2] * (z2 / (1.0f + __expf(-z2))), p3 = v[3] * rs * g[3] * (z3 / (1.0f + __expf(-z3)));
;         u32x2 w; w.x = cvt_pk_bf16(p0, p1); w.y = cvt_pk_bf16(p2, p3); *((u32x2*)(omix + (row0 + c) * DM + h * 256) + lane) = w; }
	ds_read_b128 v[14:17], v2 offset:4096
	v_and_b32_e32 v2, 64, v112
	v_add_u32_e32 v6, 64, v2
	s_waitcnt lgkmcnt(0)
	v_mul_f32_e32 v2, v15, v15
	v_mul_f32_e32 v3, v17, v17
	v_fmac_f32_e32 v2, v14, v14
	v_fmac_f32_e32 v3, v16, v16
	v_add_f32_e32 v4, v2, v3
	v_xor_b32_e32 v2, 1, v112
	v_cmp_lt_i32_e32 vcc, v2, v6
	s_nop 1
	v_cndmask_b32_e32 v2, v112, v2, vcc
	v_lshlrev_b32_e32 v8, 2, v2
	ds_bpermute_b32 v5, v8, v4
	v_lshl_add_u64 v[2:3], v[96:97], 0, v[78:79]
	v_lshlrev_b32_e32 v78, 3, v182
	s_waitcnt lgkmcnt(0)
	v_add_f32_e32 v7, v4, v5
	v_xor_b32_e32 v4, 2, v112
	v_cmp_lt_i32_e32 vcc, v4, v6
	s_nop 1
	v_cndmask_b32_e32 v4, v112, v4, vcc
	v_lshlrev_b32_e32 v9, 2, v4
	v_lshl_add_u64 v[4:5], s[40:41], 0, v[78:79]
	v_add_co_u32_e32 v4, vcc, s66, v4
	ds_bpermute_b32 v10, v9, v7
	s_nop 0
	v_addc_co_u32_e32 v5, vcc, 0, v5, vcc
	v_xor_b32_e32 v4, 4, v112
	v_cmp_lt_i32_e32 vcc, v4, v6
	s_waitcnt lgkmcnt(0)
	v_add_f32_e32 v7, v7, v10
	v_cndmask_b32_e32 v4, v112, v4, vcc
	v_lshlrev_b32_e32 v10, 2, v4
	ds_bpermute_b32 v11, v10, v7
	flat_load_dwordx4 v[2:5], v[2:3]
	s_waitcnt lgkmcnt(0)
	v_add_f32_e32 v7, v7, v11
	v_xor_b32_e32 v11, 8, v112
	v_cmp_lt_i32_e32 vcc, v11, v6
	s_nop 1
	v_cndmask_b32_e32 v11, v112, v11, vcc
	v_lshlrev_b32_e32 v11, 2, v11
	ds_bpermute_b32 v12, v11, v7
	s_waitcnt lgkmcnt(0)
	v_add_f32_e32 v7, v7, v12
	v_xor_b32_e32 v12, 16, v112
	v_cmp_lt_i32_e32 vcc, v12, v6
	s_nop 1
	v_cndmask_b32_e32 v12, v112, v12, vcc
	v_lshlrev_b32_e32 v12, 2, v12
	ds_bpermute_b32 v13, v12, v7
	s_waitcnt lgkmcnt(0)
	v_add_f32_e32 v7, v7, v13
	v_xor_b32_e32 v13, 32, v112
	v_cmp_lt_i32_e32 vcc, v13, v6
	s_nop 1
	v_cndmask_b32_e32 v6, v112, v13, vcc
	v_lshlrev_b32_e32 v13, 2, v6
	ds_bpermute_b32 v6, v13, v7
	s_waitcnt lgkmcnt(0)
	v_add_f32_e32 v6, v7, v6
	v_fmamk_f32 v6, v6, 0x3b800000, v110
	v_mul_f32_e32 v7, 0x4f800000, v6
	v_cmp_gt_f32_e32 vcc, s65, v6
	s_nop 1
	v_cndmask_b32_e32 v6, v6, v7, vcc
	v_sqrt_f32_e32 v7, v6
	s_nop 0
	v_add_u32_e32 v20, -1, v7
	v_fma_f32 v21, -v20, v7, v6
	v_cmp_ge_f32_e64 s[40:41], 0, v21
	v_add_u32_e32 v21, 1, v7
	s_nop 0
	v_cndmask_b32_e64 v20, v7, v20, s[40:41]
	v_fma_f32 v7, -v21, v7, v6
	v_cmp_lt_f32_e64 s[40:41], 0, v7
	s_nop 1
	v_cndmask_b32_e64 v7, v20, v21, s[40:41]
	v_mul_f32_e32 v20, 0x37800000, v7
	v_cndmask_b32_e32 v7, v7, v20, vcc
	v_cmp_class_f32_e32 vcc, v6, v111
	s_nop 1
	v_cndmask_b32_e32 v20, v7, v6, vcc
	v_div_scale_f32 v21, s[40:41], v20, v20, 1.0
	v_rcp_f32_e32 v22, v21
	v_lshl_add_u64 v[6:7], v[82:83], 0, s[38:39]
	v_fma_f32 v23, -v21, v22, 1.0
	v_fmac_f32_e32 v22, v23, v22
	v_div_scale_f32 v23, vcc, 1.0, v20, 1.0
	v_mul_f32_e32 v24, v23, v22
	v_fma_f32 v25, -v21, v24, v23
	v_fmac_f32_e32 v24, v25, v22
	v_fma_f32 v21, -v21, v24, v23
	v_div_fmas_f32 v21, v21, v22, v24
	s_waitcnt vmcnt(0)
	v_mov_b32_e32 v18, v126
	v_mov_b32_e32 v19, v127
	v_lshlrev_b32_e32 v22, 16, v18
	v_mul_f32_e32 v23, 0xbfb8aa3b, v22
	v_exp_f32_e32 v23, v23
	v_div_fixup_f32 v20, v21, v20, 1.0
	v_and_b32_e32 v18, 0xffff0000, v18
	v_mul_f32_e32 v14, v14, v20
	v_add_f32_e32 v21, 1.0, v23
	v_div_scale_f32 v23, s[40:41], v21, v21, v22
	v_rcp_f32_e32 v24, v23
	v_mul_f32_e32 v14, v2, v14
	v_lshlrev_b32_e32 v25, 16, v19
	v_mul_f32_e32 v15, v15, v20
	v_fma_f32 v26, -v23, v24, 1.0
	v_fmac_f32_e32 v24, v26, v24
	v_div_scale_f32 v26, vcc, v22, v21, v22
	v_mul_f32_e32 v27, v26, v24
	v_fma_f32 v28, -v23, v27, v26
	v_fmac_f32_e32 v27, v28, v24
	v_fma_f32 v23, -v23, v27, v26
	v_mul_f32_e32 v26, 0xbfb8aa3b, v18
	v_exp_f32_e32 v26, v26
	v_div_fmas_f32 v23, v23, v24, v27
	v_div_fixup_f32 v21, v23, v21, v22
	v_mul_f32_e32 v14, v21, v14
	v_add_f32_e32 v22, 1.0, v26
	v_div_scale_f32 v23, s[40:41], v22, v22, v18
	v_rcp_f32_e32 v24, v23
	v_mul_f32_e32 v15, v3, v15
	v_and_b32_e32 v19, 0xffff0000, v19
	v_mul_f32_e32 v16, v16, v20
	v_fma_f32 v21, -v23, v24, 1.0
	v_fmac_f32_e32 v24, v21, v24
	v_div_scale_f32 v21, vcc, v18, v22, v18
	v_mul_f32_e32 v26, v21, v24
	v_fma_f32 v27, -v23, v26, v21
	v_fmac_f32_e32 v26, v27, v24
	v_fma_f32 v21, -v23, v26, v21
	v_mul_f32_e32 v23, 0xbfb8aa3b, v25
	v_exp_f32_e32 v23, v23
	v_div_fmas_f32 v21, v21, v24, v26
	v_div_fixup_f32 v18, v21, v22, v18
	v_mul_f32_e32 v15, v18, v15
	v_add_f32_e32 v21, 1.0, v23
	v_div_scale_f32 v22, s[40:41], v21, v21, v25
	v_rcp_f32_e32 v23, v22
	v_mul_f32_e32 v16, v4, v16
	v_mul_f32_e32 v17, v17, v20
	v_mul_f32_e32 v17, v5, v17
	v_fma_f32 v18, -v22, v23, 1.0
	v_fmac_f32_e32 v23, v18, v23
	v_div_scale_f32 v18, vcc, v25, v21, v25
	v_mul_f32_e32 v24, v18, v23
	v_fma_f32 v26, -v22, v24, v18
	v_fmac_f32_e32 v24, v26, v23
	v_fma_f32 v18, -v22, v24, v18
	v_mul_f32_e32 v22, 0xbfb8aa3b, v19
	v_exp_f32_e32 v22, v22
	v_div_fmas_f32 v18, v18, v23, v24
	v_div_fixup_f32 v18, v18, v21, v25
	v_mul_f32_e32 v16, v18, v16
	v_add_f32_e32 v21, 1.0, v22
	v_div_scale_f32 v22, s[40:41], v21, v21, v19
	v_rcp_f32_e32 v23, v22
	s_lshl_b64 s[40:41], s[50:51], 13
	s_add_u32 s50, s48, s53
	s_addc_u32 s51, s49, 0
	v_fma_f32 v18, -v22, v23, 1.0
	v_fmac_f32_e32 v23, v18, v23
	v_div_scale_f32 v18, vcc, v19, v21, v19
	v_mul_f32_e32 v20, v18, v23
	v_fma_f32 v24, -v22, v20, v18
	v_fmac_f32_e32 v20, v24, v23
	v_fma_f32 v18, -v22, v20, v18
	v_div_fmas_f32 v18, v18, v23, v20
	v_div_fixup_f32 v18, v18, v21, v19
	v_mul_f32_e32 v17, v18, v17
	v_cvt_pk_bf16_f32 v14, v14, v15
	v_cvt_pk_bf16_f32 v15, v16, v17
	v_lshl_add_u64 v[16:17], v[6:7], 0, s[40:41]
	s_mul_i32 s40, s51, 0x3000
	s_mul_hi_u32 s41, s50, 0x3000
	s_add_i32 s41, s41, s40
	s_mul_i32 s40, s50, 0x3000
	s_add_u32 s40, s90, s40
	s_addc_u32 s41, s91, s41
	s_add_u32 s40, s40, s38
	s_addc_u32 s41, s41, 0
	v_lshl_add_u64 v[20:21], s[40:41], 0, v[78:79]
	v_add_co_u32_e32 v20, vcc, s66, v20
	global_store_dwordx2 v[16:17], v[14:15], off
	s_nop 0
	v_addc_co_u32_e32 v21, vcc, 0, v21, vcc
	v_add_u32_e32 v14, s54, v98
	ds_read_b128 v[16:19], v14 offset:4096
	s_waitcnt lgkmcnt(0)
; #define LAS __attribute__((address_space(3)))
; __device__ __forceinline__ void gc_unit(LAS unsigned char* lds, int unit, const bf16_t* proj, const bf16_t* dSt, const float* gnorm, bf16_t* omix, int tid, int wave, int lane) {
;     ...
;     for (int rr = 0; rr < 8; ++rr) { const int c = 8 * wave + rr; const f32x4 v = *(const LAS f32x4*)(lds + L_OT + c * 1040 + lane * 16);
;         float ss = (v[0] * v[0] + v[1] * v[1]) + (v[2] * v[2] + v[3] * v[3]);
; #pragma unroll
;         for (int o = 1; o < 64; o <<= 1) ss += __shfl_xor(ss, o);
;         const float rs = 1.0f / sqrtf(ss * (1.0f / 256.0f) + EPS);
	v_mul_f32_e32 v15, v17, v17
	v_mul_f32_e32 v22, v19, v19
	v_fmac_f32_e32 v15, v16, v16
	v_fmac_f32_e32 v22, v18, v18
	v_add_f32_e32 v15, v15, v22
	s_nop 1
	v_add_f32_dpp v15, v15, v15 quad_perm:[1,0,3,2] row_mask:0xf bank_mask:0xf
	s_nop 1
	v_add_f32_dpp v15, v15, v15 quad_perm:[2,3,0,1] row_mask:0xf bank_mask:0xf
	s_nop 1
	v_add_f32_dpp v15, v15, v15 row_half_mirror row_mask:0xf bank_mask:0xf
	s_nop 1
	v_add_f32_dpp v15, v15, v15 row_mirror row_mask:0xf bank_mask:0xf
	v_mov_b32_e32 v22, v15
	s_nop 1
	v_permlane16_swap_b32_e32 v15, v22
	s_nop 0
	v_add_f32_e32 v15, v15, v22
	v_mov_b32_e32 v22, v15
	s_nop 1
	v_permlane32_swap_b32_e32 v15, v22
	s_nop 0
	v_add_f32_e32 v15, v15, v22
	v_fmamk_f32 v15, v15, 0x3b800000, v110
	v_mul_f32_e32 v22, 0x4f800000, v15
	v_cmp_gt_f32_e32 vcc, s65, v15
	s_nop 1
	v_cndmask_b32_e32 v15, v15, v22, vcc
	v_sqrt_f32_e32 v22, v15
	s_nop 0
	v_add_u32_e32 v23, -1, v22
	v_fma_f32 v24, -v23, v22, v15
	v_cmp_ge_f32_e64 s[40:41], 0, v24
	v_add_u32_e32 v24, 1, v22
	s_nop 0
	v_cndmask_b32_e64 v23, v22, v23, s[40:41]
	v_fma_f32 v22, -v24, v22, v15
	v_cmp_lt_f32_e64 s[40:41], 0, v22
	s_nop 1
	v_cndmask_b32_e64 v22, v23, v24, s[40:41]
	v_mul_f32_e32 v23, 0x37800000, v22
	v_cndmask_b32_e32 v22, v22, v23, vcc
	v_cmp_class_f32_e32 vcc, v15, v111
	s_nop 1
	v_cndmask_b32_e32 v15, v22, v15, vcc
	v_div_scale_f32 v22, s[40:41], v15, v15, 1.0
	v_rcp_f32_e32 v23, v22
	s_nop 0
	v_fma_f32 v24, -v22, v23, 1.0
	v_fmac_f32_e32 v23, v24, v23
	v_div_scale_f32 v24, vcc, 1.0, v15, 1.0
	v_mul_f32_e32 v25, v24, v23
	v_fma_f32 v26, -v22, v25, v24
	v_fmac_f32_e32 v25, v26, v23
	v_fma_f32 v22, -v22, v25, v24
	v_div_fmas_f32 v22, v22, v23, v25
	v_mov_b32_e32 v20, v128
	v_mov_b32_e32 v21, v129
	v_lshlrev_b32_e32 v23, 16, v20
	v_mul_f32_e32 v24, 0xbfb8aa3b, v23
	v_exp_f32_e32 v24, v24
	v_and_b32_e32 v20, 0xffff0000, v20
	v_div_fixup_f32 v15, v22, v15, 1.0
	v_mul_f32_e32 v16, v16, v15
	v_add_f32_e32 v24, 1.0, v24
	v_div_scale_f32 v25, s[40:41], v24, v24, v23
	v_rcp_f32_e32 v26, v25
	v_mul_f32_e32 v16, v2, v16
	v_lshlrev_b32_e32 v22, 16, v21
	v_mul_f32_e32 v17, v17, v15
	v_fma_f32 v27, -v25, v26, 1.0
	v_fmac_f32_e32 v26, v27, v26
	v_div_scale_f32 v27, vcc, v23, v24, v23
	v_mul_f32_e32 v28, v27, v26
	v_fma_f32 v29, -v25, v28, v27
	v_fmac_f32_e32 v28, v29, v26
	v_fma_f32 v25, -v25, v28, v27
	v_mul_f32_e32 v27, 0xbfb8aa3b, v20
	v_exp_f32_e32 v27, v27
	v_div_fmas_f32 v25, v25, v26, v28
	v_div_fixup_f32 v23, v25, v24, v23
	v_mul_f32_e32 v16, v23, v16
	v_add_f32_e32 v24, 1.0, v27
	v_div_scale_f32 v25, s[40:41], v24, v24, v20
	v_rcp_f32_e32 v26, v25
	v_mul_f32_e32 v17, v3, v17
	v_and_b32_e32 v21, 0xffff0000, v21
	v_mul_f32_e32 v18, v18, v15
	v_fma_f32 v23, -v25, v26, 1.0
	v_fmac_f32_e32 v26, v23, v26
	v_div_scale_f32 v23, vcc, v20, v24, v20
	v_mul_f32_e32 v27, v23, v26
	v_fma_f32 v28, -v25, v27, v23
	v_fmac_f32_e32 v27, v28, v26
	v_fma_f32 v23, -v25, v27, v23
	v_mul_f32_e32 v25, 0xbfb8aa3b, v22
	v_exp_f32_e32 v25, v25
	v_div_fmas_f32 v23, v23, v26, v27
	v_div_fixup_f32 v20, v23, v24, v20
	v_mul_f32_e32 v17, v20, v17
	v_add_f32_e32 v23, 1.0, v25
	v_div_scale_f32 v24, s[40:41], v23, v23, v22
	v_rcp_f32_e32 v25, v24
	v_mul_f32_e32 v15, v19, v15
	v_mul_f32_e32 v18, v4, v18
	v_mul_f32_e32 v15, v5, v15
	v_fma_f32 v20, -v24, v25, 1.0
	v_fmac_f32_e32 v25, v20, v25
	v_div_scale_f32 v20, vcc, v22, v23, v22
	v_mul_f32_e32 v26, v20, v25
	v_fma_f32 v27, -v24, v26, v20
	v_fmac_f32_e32 v26, v27, v25
	v_fma_f32 v20, -v24, v26, v20
	v_mul_f32_e32 v24, 0xbfb8aa3b, v21
	v_exp_f32_e32 v24, v24
	v_div_fmas_f32 v20, v20, v25, v26
	v_div_fixup_f32 v20, v20, v23, v22
	v_mul_f32_e32 v18, v20, v18
	v_add_f32_e32 v22, 1.0, v24
	v_div_scale_f32 v23, s[40:41], v22, v22, v21
	v_rcp_f32_e32 v24, v23
	s_lshl_b64 s[40:41], s[50:51], 13
	s_add_u32 s50, s48, s55
	s_addc_u32 s51, s49, 0
	v_fma_f32 v19, -v23, v24, 1.0
	v_fmac_f32_e32 v24, v19, v24
	v_div_scale_f32 v19, vcc, v21, v22, v21
	v_mul_f32_e32 v20, v19, v24
	v_fma_f32 v25, -v23, v20, v19
	v_fmac_f32_e32 v20, v25, v24
	v_fma_f32 v19, -v23, v20, v19
	v_div_fmas_f32 v19, v19, v24, v20
	v_div_fixup_f32 v19, v19, v22, v21
	v_mul_f32_e32 v15, v19, v15
	v_cvt_pk_bf16_f32 v16, v16, v17
	v_cvt_pk_bf16_f32 v17, v18, v15
	v_lshl_add_u64 v[18:19], v[6:7], 0, s[40:41]
	s_mul_i32 s40, s51, 0x3000
	s_mul_hi_u32 s41, s50, 0x3000
	s_add_i32 s41, s41, s40
	s_mul_i32 s40, s50, 0x3000
	s_add_u32 s40, s90, s40
	s_addc_u32 s41, s91, s41
	s_add_u32 s40, s40, s38
	s_addc_u32 s41, s41, 0
	v_lshl_add_u64 v[20:21], s[40:41], 0, v[78:79]
	v_add_co_u32_e32 v20, vcc, s66, v20
	global_store_dwordx2 v[18:19], v[16:17], off
	s_nop 0
	v_addc_co_u32_e32 v21, vcc, 0, v21, vcc
	ds_read_b128 v[16:19], v14 offset:5136
	s_waitcnt lgkmcnt(0)
; #define LAS __attribute__((address_space(3)))
; __device__ __forceinline__ unsigned cvt_pk_bf16(float lo, float hi) { unsigned r; asm volatile("v_cvt_pk_bf16_f32 %0, %1, %2" : "=v"(r) : "v"(lo), "v"(hi)); return r; }
; __device__ __forceinline__ float bflo(unsigned w) { return __uint_as_float(w << 16); }
; __device__ __forceinline__ float bfhi(unsigned w) { return __uint_as_float(w & 0xffff0000u); }
; __device__ __forceinline__ void gc_unit(LAS unsigned char* lds, int unit, const bf16_t* proj, const bf16_t* dSt, const float* gnorm, bf16_t* omix, int tid, int wave, int lane) {
;     ...
;     for (int rr = 0; rr < 8; ++rr) { const int c = 8 * wave + rr; const f32x4 v = *(const LAS f32x4*)(lds + L_OT + c * 1040 + lane * 16);
;         float ss = (v[0] * v[0] + v[1] * v[1]) + (v[2] * v[2] + v[3] * v[3]);
; #pragma unroll
;         for (int o = 1; o < 64; o <<= 1) ss += __shfl_xor(ss, o);
;         const float rs = 1.0f / sqrtf(ss * (1.0f / 256.0f) + EPS);
;         const u32x2 gw2 = *((const u32x2*)(proj + (row0 + c) * PROJ_LD + C_GOUT + h * 256) + lane);
;         const float z0 = bflo(gw2.x), z1 = bfhi(gw2.x), z2 = bflo(gw2.y), z3 = bfhi(gw2.y);
;         const float p0 = v[0] * rs * g[0] * (z0 / (1.0f + __expf(-z0))), p1 = v[1] * rs * g[1] * (z1 / (1.0f + __expf(-z1)));
;         const float p2 = v[2] * rs * g[2] * (z2 / (1.0f + __expf(-z2))), p3 = v[3] * rs * g[3] * (z3 / (1.0f + __expf(-z3)));
;         u32x2 w; w.x = cvt_pk_bf16(p0, p1); w.y = cvt_pk_bf16(p2, p3); *((u32x2*)(omix + (row0 + c) * DM + h * 256) + lane) = w; }
	v_mul_f32_e32 v15, v17, v17
	v_mul_f32_e32 v22, v19, v19
	v_fmac_f32_e32 v15, v16, v16
	v_fmac_f32_e32 v22, v18, v18
	v_add_f32_e32 v15, v15, v22
	s_nop 1
	v_add_f32_dpp v15, v15, v15 quad_perm:[1,0,3,2] row_mask:0xf bank_mask:0xf
	s_nop 1
	v_add_f32_dpp v15, v15, v15 quad_perm:[2,3,0,1] row_mask:0xf bank_mask:0xf
	s_nop 1
	v_add_f32_dpp v15, v15, v15 row_half_mirror row_mask:0xf bank_mask:0xf
	s_nop 1
	v_add_f32_dpp v15, v15, v15 row_mirror row_mask:0xf bank_mask:0xf
	v_mov_b32_e32 v22, v15
	s_nop 1
	v_permlane16_swap_b32_e32 v15, v22
	s_nop 0
	v_add_f32_e32 v15, v15, v22
	v_mov_b32_e32 v22, v15
	s_nop 1
	v_permlane32_swap_b32_e32 v15, v22
	s_nop 0
	v_add_f32_e32 v15, v15, v22
	v_fmamk_f32 v15, v15, 0x3b800000, v110
	v_mul_f32_e32 v22, 0x4f800000, v15
	v_cmp_gt_f32_e32 vcc, s65, v15
	s_nop 1
	v_cndmask_b32_e32 v15, v15, v22, vcc
	v_sqrt_f32_e32 v22, v15
	s_nop 0
	v_add_u32_e32 v23, -1, v22
	v_fma_f32 v24, -v23, v22, v15
	v_cmp_ge_f32_e64 s[40:41], 0, v24
	v_add_u32_e32 v24, 1, v22
	s_nop 0
	v_cndmask_b32_e64 v23, v22, v23, s[40:41]
	v_fma_f32 v22, -v24, v22, v15
	v_cmp_lt_f32_e64 s[40:41], 0, v22
	s_nop 1
	v_cndmask_b32_e64 v22, v23, v24, s[40:41]
	v_mul_f32_e32 v23, 0x37800000, v22
	v_cndmask_b32_e32 v22, v22, v23, vcc
	v_cmp_class_f32_e32 vcc, v15, v111
	s_nop 1
	v_cndmask_b32_e32 v15, v22, v15, vcc
	v_div_scale_f32 v22, s[40:41], v15, v15, 1.0
	v_rcp_f32_e32 v23, v22
	s_nop 0
	v_fma_f32 v24, -v22, v23, 1.0
	v_fmac_f32_e32 v23, v24, v23
	v_div_scale_f32 v24, vcc, 1.0, v15, 1.0
	v_mul_f32_e32 v25, v24, v23
	v_fma_f32 v26, -v22, v25, v24
	v_fmac_f32_e32 v25, v26, v23
	v_fma_f32 v22, -v22, v25, v24
	v_div_fmas_f32 v22, v22, v23, v25
	v_mov_b32_e32 v20, v130
	v_mov_b32_e32 v21, v131
	v_lshlrev_b32_e32 v23, 16, v20
	v_mul_f32_e32 v24, 0xbfb8aa3b, v23
	v_exp_f32_e32 v24, v24
	v_and_b32_e32 v20, 0xffff0000, v20
	v_div_fixup_f32 v15, v22, v15, 1.0
	v_mul_f32_e32 v16, v16, v15
	v_add_f32_e32 v24, 1.0, v24
	v_div_scale_f32 v25, s[40:41], v24, v24, v23
	v_rcp_f32_e32 v26, v25
	v_mul_f32_e32 v16, v2, v16
	v_lshlrev_b32_e32 v22, 16, v21
	v_mul_f32_e32 v17, v17, v15
	v_fma_f32 v27, -v25, v26, 1.0
	v_fmac_f32_e32 v26, v27, v26
	v_div_scale_f32 v27, vcc, v23, v24, v23
	v_mul_f32_e32 v28, v27, v26
	v_fma_f32 v29, -v25, v28, v27
	v_fmac_f32_e32 v28, v29, v26
	v_fma_f32 v25, -v25, v28, v27
	v_mul_f32_e32 v27, 0xbfb8aa3b, v20
	v_exp_f32_e32 v27, v27
	v_div_fmas_f32 v25, v25, v26, v28
	v_div_fixup_f32 v23, v25, v24, v23
	v_mul_f32_e32 v16, v23, v16
	v_add_f32_e32 v24, 1.0, v27
	v_div_scale_f32 v25, s[40:41], v24, v24, v20
	v_rcp_f32_e32 v26, v25
	v_mul_f32_e32 v17, v3, v17
	v_and_b32_e32 v21, 0xffff0000, v21
	v_mul_f32_e32 v18, v18, v15
	v_fma_f32 v23, -v25, v26, 1.0
	v_fmac_f32_e32 v26, v23, v26
	v_div_scale_f32 v23, vcc, v20, v24, v20
	v_mul_f32_e32 v27, v23, v26
	v_fma_f32 v28, -v25, v27, v23
	v_fmac_f32_e32 v27, v28, v26
	v_fma_f32 v23, -v25, v27, v23
	v_mul_f32_e32 v25, 0xbfb8aa3b, v22
	v_exp_f32_e32 v25, v25
	v_div_fmas_f32 v23, v23, v26, v27
	v_div_fixup_f32 v20, v23, v24, v20
	v_mul_f32_e32 v17, v20, v17
	v_add_f32_e32 v23, 1.0, v25
	v_div_scale_f32 v24, s[40:41], v23, v23, v22
	v_rcp_f32_e32 v25, v24
	v_mul_f32_e32 v15, v19, v15
	v_mul_f32_e32 v18, v4, v18
	v_mul_f32_e32 v15, v5, v15
	v_fma_f32 v20, -v24, v25, 1.0
	v_fmac_f32_e32 v25, v20, v25
	v_div_scale_f32 v20, vcc, v22, v23, v22
	v_mul_f32_e32 v26, v20, v25
	v_fma_f32 v27, -v24, v26, v20
	v_fmac_f32_e32 v26, v27, v25
	v_fma_f32 v20, -v24, v26, v20
	v_mul_f32_e32 v24, 0xbfb8aa3b, v21
	v_exp_f32_e32 v24, v24
	v_div_fmas_f32 v20, v20, v25, v26
	v_div_fixup_f32 v20, v20, v23, v22
	v_mul_f32_e32 v18, v20, v18
	v_add_f32_e32 v22, 1.0, v24
	v_div_scale_f32 v23, s[40:41], v22, v22, v21
	v_rcp_f32_e32 v24, v23
	s_lshl_b64 s[40:41], s[50:51], 13
	s_add_u32 s50, s48, s56
	s_addc_u32 s51, s49, 0
	v_fma_f32 v19, -v23, v24, 1.0
	v_fmac_f32_e32 v24, v19, v24
	v_div_scale_f32 v19, vcc, v21, v22, v21
	v_mul_f32_e32 v20, v19, v24
	v_fma_f32 v25, -v23, v20, v19
	v_fmac_f32_e32 v20, v25, v24
	v_fma_f32 v19, -v23, v20, v19
	v_div_fmas_f32 v19, v19, v24, v20
	v_div_fixup_f32 v19, v19, v22, v21
	v_mul_f32_e32 v15, v19, v15
	v_cvt_pk_bf16_f32 v16, v16, v17
	v_cvt_pk_bf16_f32 v17, v18, v15
	v_lshl_add_u64 v[18:19], v[6:7], 0, s[40:41]
	s_mul_i32 s40, s51, 0x3000
	s_mul_hi_u32 s41, s50, 0x3000
	s_add_i32 s41, s41, s40
	s_mul_i32 s40, s50, 0x3000
	s_add_u32 s40, s90, s40
	s_addc_u32 s41, s91, s41
	s_add_u32 s40, s40, s38
	s_addc_u32 s41, s41, 0
	v_lshl_add_u64 v[20:21], s[40:41], 0, v[78:79]
	v_add_co_u32_e32 v20, vcc, s66, v20
	global_store_dwordx2 v[18:19], v[16:17], off
	s_nop 0
	v_addc_co_u32_e32 v21, vcc, 0, v21, vcc
	ds_read_b128 v[16:19], v14 offset:6176
	s_waitcnt lgkmcnt(0)
; #define LAS __attribute__((address_space(3)))
; __device__ __forceinline__ unsigned cvt_pk_bf16(float lo, float hi) { unsigned r; asm volatile("v_cvt_pk_bf16_f32 %0, %1, %2" : "=v"(r) : "v"(lo), "v"(hi)); return r; }
; __device__ __forceinline__ float bflo(unsigned w) { return __uint_as_float(w << 16); }
; __device__ __forceinline__ float bfhi(unsigned w) { return __uint_as_float(w & 0xffff0000u); }
; __device__ __forceinline__ void gc_unit(LAS unsigned char* lds, int unit, const bf16_t* proj, const bf16_t* dSt, const float* gnorm, bf16_t* omix, int tid, int wave, int lane) {
;     ...
;     for (int rr = 0; rr < 8; ++rr) { const int c = 8 * wave + rr; const f32x4 v = *(const LAS f32x4*)(lds + L_OT + c * 1040 + lane * 16);
;         float ss = (v[0] * v[0] + v[1] * v[1]) + (v[2] * v[2] + v[3] * v[3]);
; #pragma unroll
;         for (int o = 1; o < 64; o <<= 1) ss += __shfl_xor(ss, o);
;         const float rs = 1.0f / sqrtf(ss * (1.0f / 256.0f) + EPS);
;         const u32x2 gw2 = *((const u32x2*)(proj + (row0 + c) * PROJ_LD + C_GOUT + h * 256) + lane);
;         const float z0 = bflo(gw2.x), z1 = bfhi(gw2.x), z2 = bflo(gw2.y), z3 = bfhi(gw2.y);
;         const float p0 = v[0] * rs * g[0] * (z0 / (1.0f + __expf(-z0))), p1 = v[1] * rs * g[1] * (z1 / (1.0f + __expf(-z1)));
;         const float p2 = v[2] * rs * g[2] * (z2 / (1.0f + __expf(-z2))), p3 = v[3] * rs * g[3] * (z3 / (1.0f + __expf(-z3)));
;         u32x2 w; w.x = cvt_pk_bf16(p0, p1); w.y = cvt_pk_bf16(p2, p3); *((u32x2*)(omix + (row0 + c) * DM + h * 256) + lane) = w; }
	v_mul_f32_e32 v15, v17, v17
	v_mul_f32_e32 v22, v19, v19
	v_fmac_f32_e32 v15, v16, v16
	v_fmac_f32_e32 v22, v18, v18
	v_add_f32_e32 v15, v15, v22
	s_nop 1
	v_add_f32_dpp v15, v15, v15 quad_perm:[1,0,3,2] row_mask:0xf bank_mask:0xf
	s_nop 1
	v_add_f32_dpp v15, v15, v15 quad_perm:[2,3,0,1] row_mask:0xf bank_mask:0xf
	s_nop 1
	v_add_f32_dpp v15, v15, v15 row_half_mirror row_mask:0xf bank_mask:0xf
	s_nop 1
	v_add_f32_dpp v15, v15, v15 row_mirror row_mask:0xf bank_mask:0xf
	v_mov_b32_e32 v22, v15
	s_nop 1
	v_permlane16_swap_b32_e32 v15, v22
	s_nop 0
	v_add_f32_e32 v15, v15, v22
	v_mov_b32_e32 v22, v15
	s_nop 1
	v_permlane32_swap_b32_e32 v15, v22
	s_nop 0
	v_add_f32_e32 v15, v15, v22
	v_fmamk_f32 v15, v15, 0x3b800000, v110
	v_mul_f32_e32 v22, 0x4f800000, v15
	v_cmp_gt_f32_e32 vcc, s65, v15
	s_nop 1
	v_cndmask_b32_e32 v15, v15, v22, vcc
	v_sqrt_f32_e32 v22, v15
	s_nop 0
	v_add_u32_e32 v23, -1, v22
	v_fma_f32 v24, -v23, v22, v15
	v_cmp_ge_f32_e64 s[40:41], 0, v24
	v_add_u32_e32 v24, 1, v22
	s_nop 0
	v_cndmask_b32_e64 v23, v22, v23, s[40:41]
	v_fma_f32 v22, -v24, v22, v15
	v_cmp_lt_f32_e64 s[40:41], 0, v22
	s_nop 1
	v_cndmask_b32_e64 v22, v23, v24, s[40:41]
	v_mul_f32_e32 v23, 0x37800000, v22
	v_cndmask_b32_e32 v22, v22, v23, vcc
	v_cmp_class_f32_e32 vcc, v15, v111
	s_nop 1
	v_cndmask_b32_e32 v15, v22, v15, vcc
	v_div_scale_f32 v22, s[40:41], v15, v15, 1.0
	v_rcp_f32_e32 v23, v22
	s_nop 0
	v_fma_f32 v24, -v22, v23, 1.0
	v_fmac_f32_e32 v23, v24, v23
	v_div_scale_f32 v24, vcc, 1.0, v15, 1.0
	v_mul_f32_e32 v25, v24, v23
	v_fma_f32 v26, -v22, v25, v24
	v_fmac_f32_e32 v25, v26, v23
	v_fma_f32 v22, -v22, v25, v24
	v_div_fmas_f32 v22, v22, v23, v25
	v_mov_b32_e32 v20, v132
	v_mov_b32_e32 v21, v133
	v_lshlrev_b32_e32 v23, 16, v20
	v_mul_f32_e32 v24, 0xbfb8aa3b, v23
	v_exp_f32_e32 v24, v24
	v_and_b32_e32 v20, 0xffff0000, v20
	v_div_fixup_f32 v15, v22, v15, 1.0
	v_mul_f32_e32 v16, v16, v15
	v_add_f32_e32 v24, 1.0, v24
	v_div_scale_f32 v25, s[40:41], v24, v24, v23
	v_rcp_f32_e32 v26, v25
	v_mul_f32_e32 v16, v2, v16
	v_lshlrev_b32_e32 v22, 16, v21
	v_mul_f32_e32 v17, v17, v15
	v_fma_f32 v27, -v25, v26, 1.0
	v_fmac_f32_e32 v26, v27, v26
	v_div_scale_f32 v27, vcc, v23, v24, v23
	v_mul_f32_e32 v28, v27, v26
	v_fma_f32 v29, -v25, v28, v27
	v_fmac_f32_e32 v28, v29, v26
	v_fma_f32 v25, -v25, v28, v27
	v_mul_f32_e32 v27, 0xbfb8aa3b, v20
	v_exp_f32_e32 v27, v27
	v_div_fmas_f32 v25, v25, v26, v28
	v_div_fixup_f32 v23, v25, v24, v23
	v_mul_f32_e32 v16, v23, v16
	v_add_f32_e32 v24, 1.0, v27
	v_div_scale_f32 v25, s[40:41], v24, v24, v20
	v_rcp_f32_e32 v26, v25
	v_mul_f32_e32 v17, v3, v17
	v_and_b32_e32 v21, 0xffff0000, v21
	v_mul_f32_e32 v18, v18, v15
	v_fma_f32 v23, -v25, v26, 1.0
	v_fmac_f32_e32 v26, v23, v26
	v_div_scale_f32 v23, vcc, v20, v24, v20
	v_mul_f32_e32 v27, v23, v26
	v_fma_f32 v28, -v25, v27, v23
	v_fmac_f32_e32 v27, v28, v26
	v_fma_f32 v23, -v25, v27, v23
	v_mul_f32_e32 v25, 0xbfb8aa3b, v22
	v_exp_f32_e32 v25, v25
	v_div_fmas_f32 v23, v23, v26, v27
	v_div_fixup_f32 v20, v23, v24, v20
	v_mul_f32_e32 v17, v20, v17
	v_add_f32_e32 v23, 1.0, v25
	v_div_scale_f32 v24, s[40:41], v23, v23, v22
	v_rcp_f32_e32 v25, v24
	v_mul_f32_e32 v15, v19, v15
	v_mul_f32_e32 v18, v4, v18
	v_mul_f32_e32 v15, v5, v15
	v_fma_f32 v20, -v24, v25, 1.0
	v_fmac_f32_e32 v25, v20, v25
	v_div_scale_f32 v20, vcc, v22, v23, v22
	v_mul_f32_e32 v26, v20, v25
	v_fma_f32 v27, -v24, v26, v20
	v_fmac_f32_e32 v26, v27, v25
	v_fma_f32 v20, -v24, v26, v20
	v_mul_f32_e32 v24, 0xbfb8aa3b, v21
	v_exp_f32_e32 v24, v24
	v_div_fmas_f32 v20, v20, v25, v26
	v_div_fixup_f32 v20, v20, v23, v22
	v_mul_f32_e32 v18, v20, v18
	v_add_f32_e32 v22, 1.0, v24
	v_div_scale_f32 v23, s[40:41], v22, v22, v21
	v_rcp_f32_e32 v24, v23
	s_lshl_b64 s[40:41], s[50:51], 13
	s_add_u32 s50, s48, s57
	s_addc_u32 s51, s49, 0
	v_fma_f32 v19, -v23, v24, 1.0
	v_fmac_f32_e32 v24, v19, v24
	v_div_scale_f32 v19, vcc, v21, v22, v21
	v_mul_f32_e32 v20, v19, v24
	v_fma_f32 v25, -v23, v20, v19
	v_fmac_f32_e32 v20, v25, v24
	v_fma_f32 v19, -v23, v20, v19
	v_div_fmas_f32 v19, v19, v24, v20
	v_div_fixup_f32 v19, v19, v22, v21
	v_mul_f32_e32 v15, v19, v15
	v_cvt_pk_bf16_f32 v16, v16, v17
	v_cvt_pk_bf16_f32 v17, v18, v15
	v_lshl_add_u64 v[18:19], v[6:7], 0, s[40:41]
	s_mul_i32 s40, s51, 0x3000
	s_mul_hi_u32 s41, s50, 0x3000
	s_add_i32 s41, s41, s40
	s_mul_i32 s40, s50, 0x3000
	s_add_u32 s40, s90, s40
	s_addc_u32 s41, s91, s41
	s_add_u32 s40, s40, s38
	s_addc_u32 s41, s41, 0
	v_lshl_add_u64 v[20:21], s[40:41], 0, v[78:79]
	v_add_co_u32_e32 v20, vcc, s66, v20
	global_store_dwordx2 v[18:19], v[16:17], off
	s_nop 0
	v_addc_co_u32_e32 v21, vcc, 0, v21, vcc
	ds_read_b128 v[16:19], v14 offset:7216
	s_waitcnt lgkmcnt(0)
; #define LAS __attribute__((address_space(3)))
; __device__ __forceinline__ unsigned cvt_pk_bf16(float lo, float hi) { unsigned r; asm volatile("v_cvt_pk_bf16_f32 %0, %1, %2" : "=v"(r) : "v"(lo), "v"(hi)); return r; }
; __device__ __forceinline__ float bflo(unsigned w) { return __uint_as_float(w << 16); }
; __device__ __forceinline__ float bfhi(unsigned w) { return __uint_as_float(w & 0xffff0000u); }
; __device__ __forceinline__ void gc_unit(LAS unsigned char* lds, int unit, const bf16_t* proj, const bf16_t* dSt, const float* gnorm, bf16_t* omix, int tid, int wave, int lane) {
;     ...
;     for (int rr = 0; rr < 8; ++rr) { const int c = 8 * wave + rr; const f32x4 v = *(const LAS f32x4*)(lds + L_OT + c * 1040 + lane * 16);
;         float ss = (v[0] * v[0] + v[1] * v[1]) + (v[2] * v[2] + v[3] * v[3]);
; #pragma unroll
;         for (int o = 1; o < 64; o <<= 1) ss += __shfl_xor(ss, o);
;         const float rs = 1.0f / sqrtf(ss * (1.0f / 256.0f) + EPS);
;         const u32x2 gw2 = *((const u32x2*)(proj + (row0 + c) * PROJ_LD + C_GOUT + h * 256) + lane);
;         const float z0 = bflo(gw2.x), z1 = bfhi(gw2.x), z2 = bflo(gw2.y), z3 = bfhi(gw2.y);
;         const float p0 = v[0] * rs * g[0] * (z0 / (1.0f + __expf(-z0))), p1 = v[1] * rs * g[1] * (z1 / (1.0f + __expf(-z1)));
;         const float p2 = v[2] * rs * g[2] * (z2 / (1.0f + __expf(-z2))), p3 = v[3] * rs * g[3] * (z3 / (1.0f + __expf(-z3)));
;         u32x2 w; w.x = cvt_pk_bf16(p0, p1); w.y = cvt_pk_bf16(p2, p3); *((u32x2*)(omix + (row0 + c) * DM + h * 256) + lane) = w; }
	v_mul_f32_e32 v15, v17, v17
	v_mul_f32_e32 v22, v19, v19
	v_fmac_f32_e32 v15, v16, v16
	v_fmac_f32_e32 v22, v18, v18
	v_add_f32_e32 v15, v15, v22
	s_nop 1
	v_add_f32_dpp v15, v15, v15 quad_perm:[1,0,3,2] row_mask:0xf bank_mask:0xf
	s_nop 1
	v_add_f32_dpp v15, v15, v15 quad_perm:[2,3,0,1] row_mask:0xf bank_mask:0xf
	s_nop 1
	v_add_f32_dpp v15, v15, v15 row_half_mirror row_mask:0xf bank_mask:0xf
	s_nop 1
	v_add_f32_dpp v15, v15, v15 row_mirror row_mask:0xf bank_mask:0xf
	v_mov_b32_e32 v22, v15
	s_nop 1
	v_permlane16_swap_b32_e32 v15, v22
	s_nop 0
	v_add_f32_e32 v15, v15, v22
	v_mov_b32_e32 v22, v15
	s_nop 1
	v_permlane32_swap_b32_e32 v15, v22
	s_nop 0
	v_add_f32_e32 v15, v15, v22
	v_fmamk_f32 v15, v15, 0x3b800000, v110
	v_mul_f32_e32 v22, 0x4f800000, v15
	v_cmp_gt_f32_e32 vcc, s65, v15
	s_nop 1
	v_cndmask_b32_e32 v15, v15, v22, vcc
	v_sqrt_f32_e32 v22, v15
	s_nop 0
	v_add_u32_e32 v23, -1, v22
	v_fma_f32 v24, -v23, v22, v15
	v_cmp_ge_f32_e64 s[40:41], 0, v24
	v_add_u32_e32 v24, 1, v22
	s_nop 0
	v_cndmask_b32_e64 v23, v22, v23, s[40:41]
	v_fma_f32 v22, -v24, v22, v15
	v_cmp_lt_f32_e64 s[40:41], 0, v22
	s_nop 1
	v_cndmask_b32_e64 v22, v23, v24, s[40:41]
	v_mul_f32_e32 v23, 0x37800000, v22
	v_cndmask_b32_e32 v22, v22, v23, vcc
	v_cmp_class_f32_e32 vcc, v15, v111
	s_nop 1
	v_cndmask_b32_e32 v15, v22, v15, vcc
	v_div_scale_f32 v22, s[40:41], v15, v15, 1.0
	v_rcp_f32_e32 v23, v22
	s_nop 0
	v_fma_f32 v24, -v22, v23, 1.0
	v_fmac_f32_e32 v23, v24, v23
	v_div_scale_f32 v24, vcc, 1.0, v15, 1.0
	v_mul_f32_e32 v25, v24, v23
	v_fma_f32 v26, -v22, v25, v24
	v_fmac_f32_e32 v25, v26, v23
	v_fma_f32 v22, -v22, v25, v24
	v_div_fmas_f32 v22, v22, v23, v25
	v_mov_b32_e32 v20, v134
	v_mov_b32_e32 v21, v135
	v_lshlrev_b32_e32 v23, 16, v20
	v_mul_f32_e32 v24, 0xbfb8aa3b, v23
	v_exp_f32_e32 v24, v24
	v_and_b32_e32 v20, 0xffff0000, v20
	v_div_fixup_f32 v15, v22, v15, 1.0
	v_mul_f32_e32 v16, v16, v15
	v_add_f32_e32 v24, 1.0, v24
	v_div_scale_f32 v25, s[40:41], v24, v24, v23
	v_rcp_f32_e32 v26, v25
	v_mul_f32_e32 v16, v2, v16
	v_lshlrev_b32_e32 v22, 16, v21
	v_mul_f32_e32 v17, v17, v15
	v_fma_f32 v27, -v25, v26, 1.0
	v_fmac_f32_e32 v26, v27, v26
	v_div_scale_f32 v27, vcc, v23, v24, v23
	v_mul_f32_e32 v28, v27, v26
	v_fma_f32 v29, -v25, v28, v27
	v_fmac_f32_e32 v28, v29, v26
	v_fma_f32 v25, -v25, v28, v27
	v_mul_f32_e32 v27, 0xbfb8aa3b, v20
	v_exp_f32_e32 v27, v27
	v_div_fmas_f32 v25, v25, v26, v28
	v_div_fixup_f32 v23, v25, v24, v23
	v_mul_f32_e32 v16, v23, v16
	v_add_f32_e32 v24, 1.0, v27
	v_div_scale_f32 v25, s[40:41], v24, v24, v20
	v_rcp_f32_e32 v26, v25
	v_mul_f32_e32 v17, v3, v17
	v_and_b32_e32 v21, 0xffff0000, v21
	v_mul_f32_e32 v18, v18, v15
	v_fma_f32 v23, -v25, v26, 1.0
	v_fmac_f32_e32 v26, v23, v26
	v_div_scale_f32 v23, vcc, v20, v24, v20
	v_mul_f32_e32 v27, v23, v26
	v_fma_f32 v28, -v25, v27, v23
	v_fmac_f32_e32 v27, v28, v26
	v_fma_f32 v23, -v25, v27, v23
	v_mul_f32_e32 v25, 0xbfb8aa3b, v22
	v_exp_f32_e32 v25, v25
	v_div_fmas_f32 v23, v23, v26, v27
	v_div_fixup_f32 v20, v23, v24, v20
	v_mul_f32_e32 v17, v20, v17
	v_add_f32_e32 v23, 1.0, v25
	v_div_scale_f32 v24, s[40:41], v23, v23, v22
	v_rcp_f32_e32 v25, v24
	v_mul_f32_e32 v15, v19, v15
	v_mul_f32_e32 v18, v4, v18
	v_mul_f32_e32 v15, v5, v15
	v_fma_f32 v20, -v24, v25, 1.0
	v_fmac_f32_e32 v25, v20, v25
	v_div_scale_f32 v20, vcc, v22, v23, v22
	v_mul_f32_e32 v26, v20, v25
	v_fma_f32 v27, -v24, v26, v20
	v_fmac_f32_e32 v26, v27, v25
	v_fma_f32 v20, -v24, v26, v20
	v_mul_f32_e32 v24, 0xbfb8aa3b, v21
	v_exp_f32_e32 v24, v24
	v_div_fmas_f32 v20, v20, v25, v26
	v_div_fixup_f32 v20, v20, v23, v22
	v_mul_f32_e32 v18, v20, v18
	v_add_f32_e32 v22, 1.0, v24
	v_div_scale_f32 v23, s[40:41], v22, v22, v21
	v_rcp_f32_e32 v24, v23
	s_lshl_b64 s[40:41], s[50:51], 13
	s_add_u32 s50, s48, s58
	s_addc_u32 s51, s49, 0
	v_fma_f32 v19, -v23, v24, 1.0
	v_fmac_f32_e32 v24, v19, v24
	v_div_scale_f32 v19, vcc, v21, v22, v21
	v_mul_f32_e32 v20, v19, v24
	v_fma_f32 v25, -v23, v20, v19
	v_fmac_f32_e32 v20, v25, v24
	v_fma_f32 v19, -v23, v20, v19
	v_div_fmas_f32 v19, v19, v24, v20
	v_div_fixup_f32 v19, v19, v22, v21
	v_mul_f32_e32 v15, v19, v15
	v_cvt_pk_bf16_f32 v16, v16, v17
	v_cvt_pk_bf16_f32 v17, v18, v15
	v_lshl_add_u64 v[18:19], v[6:7], 0, s[40:41]
	s_mul_i32 s40, s51, 0x3000
	s_mul_hi_u32 s41, s50, 0x3000
	s_add_i32 s41, s41, s40
	s_mul_i32 s40, s50, 0x3000
	s_add_u32 s40, s90, s40
	s_addc_u32 s41, s91, s41
	s_add_u32 s40, s40, s38
	s_addc_u32 s41, s41, 0
	v_lshl_add_u64 v[20:21], s[40:41], 0, v[78:79]
	v_add_co_u32_e32 v20, vcc, s66, v20
	global_store_dwordx2 v[18:19], v[16:17], off
	s_nop 0
	v_addc_co_u32_e32 v21, vcc, 0, v21, vcc
	ds_read_b128 v[16:19], v14 offset:8256
	s_waitcnt lgkmcnt(0)
; #define LAS __attribute__((address_space(3)))
; __device__ __forceinline__ unsigned cvt_pk_bf16(float lo, float hi) { unsigned r; asm volatile("v_cvt_pk_bf16_f32 %0, %1, %2" : "=v"(r) : "v"(lo), "v"(hi)); return r; }
; __device__ __forceinline__ float bflo(unsigned w) { return __uint_as_float(w << 16); }
; __device__ __forceinline__ float bfhi(unsigned w) { return __uint_as_float(w & 0xffff0000u); }
; __device__ __forceinline__ void gc_unit(LAS unsigned char* lds, int unit, const bf16_t* proj, const bf16_t* dSt, const float* gnorm, bf16_t* omix, int tid, int wave, int lane) {
;     ...
;     for (int rr = 0; rr < 8; ++rr) { const int c = 8 * wave + rr; const f32x4 v = *(const LAS f32x4*)(lds + L_OT + c * 1040 + lane * 16);
;         float ss = (v[0] * v[0] + v[1] * v[1]) + (v[2] * v[2] + v[3] * v[3]);
; #pragma unroll
;         for (int o = 1; o < 64; o <<= 1) ss += __shfl_xor(ss, o);
;         const float rs = 1.0f / sqrtf(ss * (1.0f / 256.0f) + EPS);
;         const u32x2 gw2 = *((const u32x2*)(proj + (row0 + c) * PROJ_LD + C_GOUT + h * 256) + lane);
;         const float z0 = bflo(gw2.x), z1 = bfhi(gw2.x), z2 = bflo(gw2.y), z3 = bfhi(gw2.y);
;         const float p0 = v[0] * rs * g[0] * (z0 / (1.0f + __expf(-z0))), p1 = v[1] * rs * g[1] * (z1 / (1.0f + __expf(-z1)));
;         const float p2 = v[2] * rs * g[2] * (z2 / (1.0f + __expf(-z2))), p3 = v[3] * rs * g[3] * (z3 / (1.0f + __expf(-z3)));
;         u32x2 w; w.x = cvt_pk_bf16(p0, p1); w.y = cvt_pk_bf16(p2, p3); *((u32x2*)(omix + (row0 + c) * DM + h * 256) + lane) = w; }
	v_mul_f32_e32 v15, v17, v17
	v_mul_f32_e32 v22, v19, v19
	v_fmac_f32_e32 v15, v16, v16
	v_fmac_f32_e32 v22, v18, v18
	v_add_f32_e32 v15, v15, v22
	s_nop 1
	v_add_f32_dpp v15, v15, v15 quad_perm:[1,0,3,2] row_mask:0xf bank_mask:0xf
	s_nop 1
	v_add_f32_dpp v15, v15, v15 quad_perm:[2,3,0,1] row_mask:0xf bank_mask:0xf
	s_nop 1
	v_add_f32_dpp v15, v15, v15 row_half_mirror row_mask:0xf bank_mask:0xf
	s_nop 1
	v_add_f32_dpp v15, v15, v15 row_mirror row_mask:0xf bank_mask:0xf
	v_mov_b32_e32 v22, v15
	s_nop 1
	v_permlane16_swap_b32_e32 v15, v22
	s_nop 0
	v_add_f32_e32 v15, v15, v22
	v_mov_b32_e32 v22, v15
	s_nop 1
	v_permlane32_swap_b32_e32 v15, v22
	s_nop 0
	v_add_f32_e32 v15, v15, v22
	v_fmamk_f32 v15, v15, 0x3b800000, v110
	v_mul_f32_e32 v22, 0x4f800000, v15
	v_cmp_gt_f32_e32 vcc, s65, v15
	s_nop 1
	v_cndmask_b32_e32 v15, v15, v22, vcc
	v_sqrt_f32_e32 v22, v15
	s_nop 0
	v_add_u32_e32 v23, -1, v22
	v_fma_f32 v24, -v23, v22, v15
	v_cmp_ge_f32_e64 s[40:41], 0, v24
	v_add_u32_e32 v24, 1, v22
	s_nop 0
	v_cndmask_b32_e64 v23, v22, v23, s[40:41]
	v_fma_f32 v22, -v24, v22, v15
	v_cmp_lt_f32_e64 s[40:41], 0, v22
	s_nop 1
	v_cndmask_b32_e64 v22, v23, v24, s[40:41]
	v_mul_f32_e32 v23, 0x37800000, v22
	v_cndmask_b32_e32 v22, v22, v23, vcc
	v_cmp_class_f32_e32 vcc, v15, v111
	s_nop 1
	v_cndmask_b32_e32 v15, v22, v15, vcc
	v_div_scale_f32 v22, s[40:41], v15, v15, 1.0
	v_rcp_f32_e32 v23, v22
	s_nop 0
	v_fma_f32 v24, -v22, v23, 1.0
	v_fmac_f32_e32 v23, v24, v23
	v_div_scale_f32 v24, vcc, 1.0, v15, 1.0
	v_mul_f32_e32 v25, v24, v23
	v_fma_f32 v26, -v22, v25, v24
	v_fmac_f32_e32 v25, v26, v23
	v_fma_f32 v22, -v22, v25, v24
	v_div_fmas_f32 v22, v22, v23, v25
	v_mov_b32_e32 v20, v136
	v_mov_b32_e32 v21, v137
	v_lshlrev_b32_e32 v23, 16, v20
	v_mul_f32_e32 v24, 0xbfb8aa3b, v23
	v_exp_f32_e32 v24, v24
	v_and_b32_e32 v20, 0xffff0000, v20
	v_div_fixup_f32 v15, v22, v15, 1.0
	v_mul_f32_e32 v16, v16, v15
	v_add_f32_e32 v24, 1.0, v24
	v_div_scale_f32 v25, s[40:41], v24, v24, v23
	v_rcp_f32_e32 v26, v25
	v_mul_f32_e32 v16, v2, v16
	v_lshlrev_b32_e32 v22, 16, v21
	v_mul_f32_e32 v17, v17, v15
	v_fma_f32 v27, -v25, v26, 1.0
	v_fmac_f32_e32 v26, v27, v26
	v_div_scale_f32 v27, vcc, v23, v24, v23
	v_mul_f32_e32 v28, v27, v26
	v_fma_f32 v29, -v25, v28, v27
	v_fmac_f32_e32 v28, v29, v26
	v_fma_f32 v25, -v25, v28, v27
	v_mul_f32_e32 v27, 0xbfb8aa3b, v20
	v_exp_f32_e32 v27, v27
	v_div_fmas_f32 v25, v25, v26, v28
	v_div_fixup_f32 v23, v25, v24, v23
	v_mul_f32_e32 v16, v23, v16
	v_add_f32_e32 v24, 1.0, v27
	v_div_scale_f32 v25, s[40:41], v24, v24, v20
	v_rcp_f32_e32 v26, v25
	v_mul_f32_e32 v17, v3, v17
	v_and_b32_e32 v21, 0xffff0000, v21
	v_mul_f32_e32 v18, v18, v15
	v_fma_f32 v23, -v25, v26, 1.0
	v_fmac_f32_e32 v26, v23, v26
	v_div_scale_f32 v23, vcc, v20, v24, v20
	v_mul_f32_e32 v27, v23, v26
	v_fma_f32 v28, -v25, v27, v23
	v_fmac_f32_e32 v27, v28, v26
	v_fma_f32 v23, -v25, v27, v23
	v_mul_f32_e32 v25, 0xbfb8aa3b, v22
	v_exp_f32_e32 v25, v25
	v_div_fmas_f32 v23, v23, v26, v27
	v_div_fixup_f32 v20, v23, v24, v20
	v_mul_f32_e32 v17, v20, v17
	v_add_f32_e32 v23, 1.0, v25
	v_div_scale_f32 v24, s[40:41], v23, v23, v22
	v_rcp_f32_e32 v25, v24
	v_mul_f32_e32 v15, v19, v15
	v_mul_f32_e32 v18, v4, v18
	v_mul_f32_e32 v15, v5, v15
	v_fma_f32 v20, -v24, v25, 1.0
	v_fmac_f32_e32 v25, v20, v25
	v_div_scale_f32 v20, vcc, v22, v23, v22
	v_mul_f32_e32 v26, v20, v25
	v_fma_f32 v27, -v24, v26, v20
	v_fmac_f32_e32 v26, v27, v25
	v_fma_f32 v20, -v24, v26, v20
	v_mul_f32_e32 v24, 0xbfb8aa3b, v21
	v_exp_f32_e32 v24, v24
	v_div_fmas_f32 v20, v20, v25, v26
	v_div_fixup_f32 v20, v20, v23, v22
	v_mul_f32_e32 v18, v20, v18
	v_add_f32_e32 v22, 1.0, v24
	v_div_scale_f32 v23, s[40:41], v22, v22, v21
	v_rcp_f32_e32 v24, v23
	s_lshl_b64 s[40:41], s[50:51], 13
	s_add_u32 s50, s48, s59
	s_addc_u32 s51, s49, 0
	v_fma_f32 v19, -v23, v24, 1.0
	v_fmac_f32_e32 v24, v19, v24
	v_div_scale_f32 v19, vcc, v21, v22, v21
	v_mul_f32_e32 v20, v19, v24
	v_fma_f32 v25, -v23, v20, v19
	v_fmac_f32_e32 v20, v25, v24
	v_fma_f32 v19, -v23, v20, v19
	v_div_fmas_f32 v19, v19, v24, v20
	v_div_fixup_f32 v19, v19, v22, v21
	v_mul_f32_e32 v15, v19, v15
	v_cvt_pk_bf16_f32 v16, v16, v17
	v_cvt_pk_bf16_f32 v17, v18, v15
	v_lshl_add_u64 v[18:19], v[6:7], 0, s[40:41]
	s_mul_i32 s40, s51, 0x3000
	s_mul_hi_u32 s41, s50, 0x3000
	s_add_i32 s41, s41, s40
	s_mul_i32 s40, s50, 0x3000
	s_add_u32 s40, s90, s40
	s_addc_u32 s41, s91, s41
	s_add_u32 s40, s40, s38
	s_addc_u32 s41, s41, 0
	v_lshl_add_u64 v[20:21], s[40:41], 0, v[78:79]
	v_add_co_u32_e32 v20, vcc, s66, v20
	global_store_dwordx2 v[18:19], v[16:17], off
	s_nop 0
	v_addc_co_u32_e32 v21, vcc, 0, v21, vcc
	ds_read_b128 v[16:19], v14 offset:9296
	s_waitcnt lgkmcnt(0)
; #define LAS __attribute__((address_space(3)))
; __device__ __forceinline__ unsigned cvt_pk_bf16(float lo, float hi) { unsigned r; asm volatile("v_cvt_pk_bf16_f32 %0, %1, %2" : "=v"(r) : "v"(lo), "v"(hi)); return r; }
; __device__ __forceinline__ float bflo(unsigned w) { return __uint_as_float(w << 16); }
; __device__ __forceinline__ float bfhi(unsigned w) { return __uint_as_float(w & 0xffff0000u); }
; __device__ __forceinline__ void gc_unit(LAS unsigned char* lds, int unit, const bf16_t* proj, const bf16_t* dSt, const float* gnorm, bf16_t* omix, int tid, int wave, int lane) {
;     ...
;     for (int rr = 0; rr < 8; ++rr) { const int c = 8 * wave + rr; const f32x4 v = *(const LAS f32x4*)(lds + L_OT + c * 1040 + lane * 16);
;         float ss = (v[0] * v[0] + v[1] * v[1]) + (v[2] * v[2] + v[3] * v[3]);
; #pragma unroll
;         for (int o = 1; o < 64; o <<= 1) ss += __shfl_xor(ss, o);
;         const float rs = 1.0f / sqrtf(ss * (1.0f / 256.0f) + EPS);
;         const u32x2 gw2 = *((const u32x2*)(proj + (row0 + c) * PROJ_LD + C_GOUT + h * 256) + lane);
;         const float z0 = bflo(gw2.x), z1 = bfhi(gw2.x), z2 = bflo(gw2.y), z3 = bfhi(gw2.y);
;         const float p0 = v[0] * rs * g[0] * (z0 / (1.0f + __expf(-z0))), p1 = v[1] * rs * g[1] * (z1 / (1.0f + __expf(-z1)));
;         const float p2 = v[2] * rs * g[2] * (z2 / (1.0f + __expf(-z2))), p3 = v[3] * rs * g[3] * (z3 / (1.0f + __expf(-z3)));
;         u32x2 w; w.x = cvt_pk_bf16(p0, p1); w.y = cvt_pk_bf16(p2, p3); *((u32x2*)(omix + (row0 + c) * DM + h * 256) + lane) = w; }
	v_mul_f32_e32 v15, v17, v17
	v_mul_f32_e32 v22, v19, v19
	v_fmac_f32_e32 v15, v16, v16
	v_fmac_f32_e32 v22, v18, v18
	v_add_f32_e32 v15, v15, v22
	s_nop 1
	v_add_f32_dpp v15, v15, v15 quad_perm:[1,0,3,2] row_mask:0xf bank_mask:0xf
	s_nop 1
	v_add_f32_dpp v15, v15, v15 quad_perm:[2,3,0,1] row_mask:0xf bank_mask:0xf
	s_nop 1
	v_add_f32_dpp v15, v15, v15 row_half_mirror row_mask:0xf bank_mask:0xf
	s_nop 1
	v_add_f32_dpp v15, v15, v15 row_mirror row_mask:0xf bank_mask:0xf
	v_mov_b32_e32 v22, v15
	s_nop 1
	v_permlane16_swap_b32_e32 v15, v22
	s_nop 0
	v_add_f32_e32 v15, v15, v22
	v_mov_b32_e32 v22, v15
	s_nop 1
	v_permlane32_swap_b32_e32 v15, v22
	s_nop 0
	v_add_f32_e32 v15, v15, v22
	v_fmamk_f32 v15, v15, 0x3b800000, v110
	v_mul_f32_e32 v22, 0x4f800000, v15
	v_cmp_gt_f32_e32 vcc, s65, v15
	s_nop 1
	v_cndmask_b32_e32 v15, v15, v22, vcc
	v_sqrt_f32_e32 v22, v15
	s_nop 0
	v_add_u32_e32 v23, -1, v22
	v_fma_f32 v24, -v23, v22, v15
	v_cmp_ge_f32_e64 s[40:41], 0, v24
	v_add_u32_e32 v24, 1, v22
	s_nop 0
	v_cndmask_b32_e64 v23, v22, v23, s[40:41]
	v_fma_f32 v22, -v24, v22, v15
	v_cmp_lt_f32_e64 s[40:41], 0, v22
	s_nop 1
	v_cndmask_b32_e64 v22, v23, v24, s[40:41]
	v_mul_f32_e32 v23, 0x37800000, v22
	v_cndmask_b32_e32 v22, v22, v23, vcc
	v_cmp_class_f32_e32 vcc, v15, v111
	s_nop 1
	v_cndmask_b32_e32 v15, v22, v15, vcc
	v_div_scale_f32 v22, s[40:41], v15, v15, 1.0
	v_rcp_f32_e32 v23, v22
	s_nop 0
	v_fma_f32 v24, -v22, v23, 1.0
	v_fmac_f32_e32 v23, v24, v23
	v_div_scale_f32 v24, vcc, 1.0, v15, 1.0
	v_mul_f32_e32 v25, v24, v23
	v_fma_f32 v26, -v22, v25, v24
	v_fmac_f32_e32 v25, v26, v23
	v_fma_f32 v22, -v22, v25, v24
	v_div_fmas_f32 v22, v22, v23, v25
	v_mov_b32_e32 v20, v138
	v_mov_b32_e32 v21, v139
	v_lshlrev_b32_e32 v23, 16, v20
	v_mul_f32_e32 v24, 0xbfb8aa3b, v23
	v_exp_f32_e32 v24, v24
	v_and_b32_e32 v20, 0xffff0000, v20
	v_div_fixup_f32 v15, v22, v15, 1.0
	v_mul_f32_e32 v16, v16, v15
	v_add_f32_e32 v24, 1.0, v24
	v_div_scale_f32 v25, s[40:41], v24, v24, v23
	v_rcp_f32_e32 v26, v25
	v_mul_f32_e32 v16, v2, v16
	v_lshlrev_b32_e32 v22, 16, v21
	v_mul_f32_e32 v17, v17, v15
	v_fma_f32 v27, -v25, v26, 1.0
	v_fmac_f32_e32 v26, v27, v26
	v_div_scale_f32 v27, vcc, v23, v24, v23
	v_mul_f32_e32 v28, v27, v26
	v_fma_f32 v29, -v25, v28, v27
	v_fmac_f32_e32 v28, v29, v26
	v_fma_f32 v25, -v25, v28, v27
	v_mul_f32_e32 v27, 0xbfb8aa3b, v20
	v_exp_f32_e32 v27, v27
	v_div_fmas_f32 v25, v25, v26, v28
	v_div_fixup_f32 v23, v25, v24, v23
	v_mul_f32_e32 v16, v23, v16
	v_add_f32_e32 v24, 1.0, v27
	v_div_scale_f32 v25, s[40:41], v24, v24, v20
	v_rcp_f32_e32 v26, v25
	v_mul_f32_e32 v17, v3, v17
	v_and_b32_e32 v21, 0xffff0000, v21
	v_mul_f32_e32 v18, v18, v15
	v_fma_f32 v23, -v25, v26, 1.0
	v_fmac_f32_e32 v26, v23, v26
	v_div_scale_f32 v23, vcc, v20, v24, v20
	v_mul_f32_e32 v27, v23, v26
	v_fma_f32 v28, -v25, v27, v23
	v_fmac_f32_e32 v27, v28, v26
	v_fma_f32 v23, -v25, v27, v23
	v_mul_f32_e32 v25, 0xbfb8aa3b, v22
	v_exp_f32_e32 v25, v25
	v_div_fmas_f32 v23, v23, v26, v27
	v_div_fixup_f32 v20, v23, v24, v20
	v_mul_f32_e32 v17, v20, v17
	v_add_f32_e32 v23, 1.0, v25
	v_div_scale_f32 v24, s[40:41], v23, v23, v22
	v_rcp_f32_e32 v25, v24
	v_mul_f32_e32 v15, v19, v15
	v_mul_f32_e32 v18, v4, v18
	v_mul_f32_e32 v15, v5, v15
	v_fma_f32 v20, -v24, v25, 1.0
	v_fmac_f32_e32 v25, v20, v25
	v_div_scale_f32 v20, vcc, v22, v23, v22
	v_mul_f32_e32 v26, v20, v25
	v_fma_f32 v27, -v24, v26, v20
	v_fmac_f32_e32 v26, v27, v25
	v_fma_f32 v20, -v24, v26, v20
	v_mul_f32_e32 v24, 0xbfb8aa3b, v21
	v_exp_f32_e32 v24, v24
	v_div_fmas_f32 v20, v20, v25, v26
	v_div_fixup_f32 v20, v20, v23, v22
	v_mul_f32_e32 v18, v20, v18
	v_add_f32_e32 v22, 1.0, v24
	v_div_scale_f32 v23, s[40:41], v22, v22, v21
	v_rcp_f32_e32 v24, v23
	s_lshl_b64 s[40:41], s[50:51], 13
	s_add_u32 s48, s48, s60
	s_addc_u32 s49, s49, 0
	v_fma_f32 v19, -v23, v24, 1.0
	v_fmac_f32_e32 v24, v19, v24
	v_div_scale_f32 v19, vcc, v21, v22, v21
	v_mul_f32_e32 v20, v19, v24
	v_fma_f32 v25, -v23, v20, v19
	v_fmac_f32_e32 v20, v25, v24
	v_fma_f32 v19, -v23, v20, v19
	v_div_fmas_f32 v19, v19, v24, v20
	v_div_fixup_f32 v19, v19, v22, v21
	v_mul_f32_e32 v15, v19, v15
	v_cvt_pk_bf16_f32 v16, v16, v17
	v_cvt_pk_bf16_f32 v17, v18, v15
	v_lshl_add_u64 v[18:19], v[6:7], 0, s[40:41]
	s_mul_i32 s40, s49, 0x3000
	s_mul_hi_u32 s41, s48, 0x3000
	s_add_i32 s41, s41, s40
	s_mul_i32 s40, s48, 0x3000
	s_add_u32 s40, s90, s40
	s_addc_u32 s41, s91, s41
	s_add_u32 s40, s40, s38
	s_addc_u32 s41, s41, 0
	global_store_dwordx2 v[18:19], v[16:17], off
	v_lshl_add_u64 v[18:19], s[40:41], 0, v[78:79]
	v_add_co_u32_e32 v18, vcc, s66, v18
	ds_read_b128 v[14:17], v14 offset:10336
	s_nop 0
	v_addc_co_u32_e32 v19, vcc, 0, v19, vcc
	s_add_i32 s94, s94, s88
	s_waitcnt lgkmcnt(0)
; #define LAS __attribute__((address_space(3)))
; __device__ __forceinline__ unsigned cvt_pk_bf16(float lo, float hi) { unsigned r; asm volatile("v_cvt_pk_bf16_f32 %0, %1, %2" : "=v"(r) : "v"(lo), "v"(hi)); return r; }
; __device__ __forceinline__ float bflo(unsigned w) { return __uint_as_float(w << 16); }
; __device__ __forceinline__ float bfhi(unsigned w) { return __uint_as_float(w & 0xffff0000u); }
; __device__ __forceinline__ void gc_unit(LAS unsigned char* lds, int unit, const bf16_t* proj, const bf16_t* dSt, const float* gnorm, bf16_t* omix, int tid, int wave, int lane) {
;     ...
;     for (int rr = 0; rr < 8; ++rr) { const int c = 8 * wave + rr; const f32x4 v = *(const LAS f32x4*)(lds + L_OT + c * 1040 + lane * 16);
;         float ss = (v[0] * v[0] + v[1] * v[1]) + (v[2] * v[2] + v[3] * v[3]);
; #pragma unroll
;         for (int o = 1; o < 64; o <<= 1) ss += __shfl_xor(ss, o);
;         const float rs = 1.0f / sqrtf(ss * (1.0f / 256.0f) + EPS);
;         const u32x2 gw2 = *((const u32x2*)(proj + (row0 + c) * PROJ_LD + C_GOUT + h * 256) + lane);
;         const float z0 = bflo(gw2.x), z1 = bfhi(gw2.x), z2 = bflo(gw2.y), z3 = bfhi(gw2.y);
;         const float p0 = v[0] * rs * g[0] * (z0 / (1.0f + __expf(-z0))), p1 = v[1] * rs * g[1] * (z1 / (1.0f + __expf(-z1)));
;         const float p2 = v[2] * rs * g[2] * (z2 / (1.0f + __expf(-z2))), p3 = v[3] * rs * g[3] * (z3 / (1.0f + __expf(-z3)));
;         u32x2 w; w.x = cvt_pk_bf16(p0, p1); w.y = cvt_pk_bf16(p2, p3); *((u32x2*)(omix + (row0 + c) * DM + h * 256) + lane) = w; }
	v_mul_f32_e32 v20, v15, v15
	v_mul_f32_e32 v21, v17, v17
	v_fmac_f32_e32 v20, v14, v14
	v_fmac_f32_e32 v21, v16, v16
	v_add_f32_e32 v20, v20, v21
	ds_bpermute_b32 v8, v8, v20
	s_add_i32 s61, s61, s62
	s_waitcnt lgkmcnt(0)
	v_add_f32_e32 v8, v20, v8
	ds_bpermute_b32 v9, v9, v8
	s_waitcnt lgkmcnt(0)
	v_add_f32_e32 v8, v8, v9
	ds_bpermute_b32 v9, v10, v8
	s_waitcnt lgkmcnt(0)
	v_add_f32_e32 v8, v8, v9
	ds_bpermute_b32 v9, v11, v8
	s_waitcnt lgkmcnt(0)
	v_add_f32_e32 v8, v8, v9
	ds_bpermute_b32 v9, v12, v8
	s_waitcnt lgkmcnt(0)
	v_add_f32_e32 v8, v8, v9
	ds_bpermute_b32 v9, v13, v8
	s_waitcnt lgkmcnt(0)
	v_add_f32_e32 v8, v8, v9
	v_fmamk_f32 v8, v8, 0x3b800000, v110
	v_mul_f32_e32 v9, 0x4f800000, v8
	v_cmp_gt_f32_e32 vcc, s65, v8
	s_nop 1
	v_cndmask_b32_e32 v8, v8, v9, vcc
	v_sqrt_f32_e32 v9, v8
	s_nop 0
	v_add_u32_e32 v10, -1, v9
	v_fma_f32 v11, -v10, v9, v8
	v_cmp_ge_f32_e64 s[40:41], 0, v11
	v_add_u32_e32 v11, 1, v9
	s_nop 0
	v_cndmask_b32_e64 v10, v9, v10, s[40:41]
	v_fma_f32 v9, -v11, v9, v8
	v_cmp_lt_f32_e64 s[40:41], 0, v9
	s_nop 1
	v_cndmask_b32_e64 v9, v10, v11, s[40:41]
	v_mul_f32_e32 v10, 0x37800000, v9
	v_cndmask_b32_e32 v9, v9, v10, vcc
	v_cmp_class_f32_e32 vcc, v8, v111
	s_nop 1
	v_cndmask_b32_e32 v8, v9, v8, vcc
	v_div_scale_f32 v9, s[40:41], v8, v8, 1.0
	v_rcp_f32_e32 v10, v9
	s_nop 0
	v_fma_f32 v11, -v9, v10, 1.0
	v_fmac_f32_e32 v10, v11, v10
	v_div_scale_f32 v11, vcc, 1.0, v8, 1.0
	v_mul_f32_e32 v12, v11, v10
	v_fma_f32 v13, -v9, v12, v11
	v_fmac_f32_e32 v12, v13, v10
	v_fma_f32 v9, -v9, v12, v11
	v_div_fmas_f32 v9, v9, v10, v12
	v_mov_b32_e32 v18, v140
	v_mov_b32_e32 v19, v141
	v_lshlrev_b32_e32 v10, 16, v18
	v_mul_f32_e32 v11, 0xbfb8aa3b, v10
	v_exp_f32_e32 v11, v11
	v_div_fixup_f32 v8, v9, v8, 1.0
	v_and_b32_e32 v9, 0xffff0000, v18
	v_mul_f32_e32 v14, v14, v8
	v_add_f32_e32 v11, 1.0, v11
	v_div_scale_f32 v13, s[40:41], v11, v11, v10
	v_rcp_f32_e32 v18, v13
	v_mul_f32_e32 v2, v2, v14
	v_lshlrev_b32_e32 v12, 16, v19
	v_and_b32_e32 v19, 0xffff0000, v19
	v_fma_f32 v14, -v13, v18, 1.0
	v_fmac_f32_e32 v18, v14, v18
	v_div_scale_f32 v14, vcc, v10, v11, v10
	v_mul_f32_e32 v20, v14, v18
	v_fma_f32 v21, -v13, v20, v14
	v_fmac_f32_e32 v20, v21, v18
	v_fma_f32 v13, -v13, v20, v14
	v_mul_f32_e32 v14, 0xbfb8aa3b, v9
	v_exp_f32_e32 v14, v14
	v_div_fmas_f32 v13, v13, v18, v20
	v_div_fixup_f32 v10, v13, v11, v10
	v_mul_f32_e32 v2, v10, v2
	v_add_f32_e32 v11, 1.0, v14
	v_div_scale_f32 v13, s[40:41], v11, v11, v9
	v_rcp_f32_e32 v14, v13
	v_mul_f32_e32 v10, v15, v8
	v_mul_f32_e32 v3, v3, v10
	v_fma_f32 v10, -v13, v14, 1.0
	v_fmac_f32_e32 v14, v10, v14
	v_div_scale_f32 v10, vcc, v9, v11, v9
	v_mul_f32_e32 v15, v10, v14
	v_fma_f32 v18, -v13, v15, v10
	v_fmac_f32_e32 v15, v18, v14
	v_fma_f32 v10, -v13, v15, v10
	v_mul_f32_e32 v13, 0xbfb8aa3b, v12
	v_exp_f32_e32 v13, v13
	v_div_fmas_f32 v10, v10, v14, v15
	v_div_fixup_f32 v9, v10, v11, v9
	v_mul_f32_e32 v3, v9, v3
	v_add_f32_e32 v10, 1.0, v13
	v_div_scale_f32 v11, s[40:41], v10, v10, v12
	v_rcp_f32_e32 v13, v11
	v_mul_f32_e32 v9, v16, v8
	v_mul_f32_e32 v4, v4, v9
	v_mul_f32_e32 v8, v17, v8
	v_fma_f32 v9, -v11, v13, 1.0
	v_fmac_f32_e32 v13, v9, v13
	v_div_scale_f32 v9, vcc, v12, v10, v12
	v_mul_f32_e32 v14, v9, v13
	v_fma_f32 v15, -v11, v14, v9
	v_fmac_f32_e32 v14, v15, v13
	v_fma_f32 v9, -v11, v14, v9
	v_mul_f32_e32 v11, 0xbfb8aa3b, v19
	v_exp_f32_e32 v11, v11
	v_div_fmas_f32 v9, v9, v13, v14
	v_div_fixup_f32 v9, v9, v10, v12
	v_mul_f32_e32 v5, v5, v8
	v_add_f32_e32 v10, 1.0, v11
	v_div_scale_f32 v11, s[40:41], v10, v10, v19
	v_rcp_f32_e32 v12, v11
	v_mul_f32_e32 v4, v9, v4
	s_lshl_b64 s[40:41], s[48:49], 13
	v_cvt_pk_bf16_f32 v2, v2, v3
	v_fma_f32 v8, -v11, v12, 1.0
	v_fmac_f32_e32 v12, v8, v12
	v_div_scale_f32 v8, vcc, v19, v10, v19
	v_mul_f32_e32 v9, v8, v12
	v_fma_f32 v13, -v11, v9, v8
	v_fmac_f32_e32 v9, v13, v12
	v_fma_f32 v8, -v11, v9, v8
	v_div_fmas_f32 v8, v8, v12, v9
	v_div_fixup_f32 v8, v8, v10, v19
	v_mul_f32_e32 v5, v8, v5
	v_cvt_pk_bf16_f32 v3, v4, v5
	v_lshl_add_u64 v[4:5], v[6:7], 0, s[40:41]
	s_cmpk_lt_i32 s94, 0x800
	global_store_dwordx2 v[4:5], v[2:3], off
	s_barrier
	s_cbranch_scc0 .LBB0_1022
